# sample-row V half hand-scheduled as a rolling 16-row pipeline across its four 16-pair blocks
# baseline (speedup 1.0000x reference)
;     ...
;     for (int j0 = 0; j0 < NTL * 16; j0 += 16) {
;         u32x4_t w[16]; float cj[16];
; #pragma unroll
;         for (int jj = 0; jj < 16; ++jj) { const u32x2_t pr = pl[j0 + jj]; const int ej = __builtin_amdgcn_readfirstlane((int)pr.x); cj[jj] = __uint_as_float(pr.y);
;             w[jj] = *(const u32x4_t*)(v8 + (size_t)ej * D + 16 * lane); }
; #pragma unroll
;         for (int jj = 0; jj < 16; ++jj) { const float c = cj[jj];
; #pragma unroll
;             for (int q = 0; q < 4; ++q) { const f32x2_t lo = __builtin_amdgcn_cvt_pk_f32_fp8((int)w[jj][q], false), hi = __builtin_amdgcn_cvt_pk_f32_fp8((int)w[jj][q], true);
;                 o[4 * q] += c * lo[0]; o[4 * q + 1] += c * lo[1]; o[4 * q + 2] += c * hi[0]; o[4 * q + 3] += c * hi[1]; } }
.LBB0_1138:
	v_mov_b32_e32 v164, s27
	ds_read_b128 v[18:21], v164 offset:0
	ds_read_b128 v[22:25], v164 offset:16
	ds_read_b128 v[26:29], v164 offset:32
	ds_read_b128 v[30:33], v164 offset:48
	ds_read_b128 v[34:37], v164 offset:64
	ds_read_b128 v[38:41], v164 offset:80
	ds_read_b128 v[42:45], v164 offset:96
	ds_read_b128 v[46:49], v164 offset:112
	s_waitcnt lgkmcnt(0)
	v_readfirstlane_b32 s30, v18
	s_ashr_i32 s31, s30, 31
	s_lshl_b64 s[30:31], s[30:31], 10
	v_lshl_add_u64 v[162:163], v[122:123], 0, s[30:31]
	global_load_dwordx4 v[68:71], v[162:163], off
	v_readfirstlane_b32 s30, v20
	s_ashr_i32 s31, s30, 31
	s_lshl_b64 s[30:31], s[30:31], 10
	v_lshl_add_u64 v[162:163], v[122:123], 0, s[30:31]
	global_load_dwordx4 v[72:75], v[162:163], off
	v_readfirstlane_b32 s30, v22
	s_ashr_i32 s31, s30, 31
	s_lshl_b64 s[30:31], s[30:31], 10
	v_lshl_add_u64 v[162:163], v[122:123], 0, s[30:31]
	global_load_dwordx4 v[76:79], v[162:163], off
	v_readfirstlane_b32 s30, v24
	s_ashr_i32 s31, s30, 31
	s_lshl_b64 s[30:31], s[30:31], 10
	v_lshl_add_u64 v[162:163], v[122:123], 0, s[30:31]
	global_load_dwordx4 v[80:83], v[162:163], off
	v_readfirstlane_b32 s30, v26
	s_ashr_i32 s31, s30, 31
	s_lshl_b64 s[30:31], s[30:31], 10
	v_lshl_add_u64 v[162:163], v[122:123], 0, s[30:31]
	global_load_dwordx4 v[84:87], v[162:163], off
	v_readfirstlane_b32 s30, v28
	s_ashr_i32 s31, s30, 31
	s_lshl_b64 s[30:31], s[30:31], 10
	v_lshl_add_u64 v[162:163], v[122:123], 0, s[30:31]
	global_load_dwordx4 v[88:91], v[162:163], off
	v_readfirstlane_b32 s30, v30
	s_ashr_i32 s31, s30, 31
	s_lshl_b64 s[30:31], s[30:31], 10
	v_lshl_add_u64 v[162:163], v[122:123], 0, s[30:31]
	global_load_dwordx4 v[92:95], v[162:163], off
	v_readfirstlane_b32 s30, v32
	s_ashr_i32 s31, s30, 31
	s_lshl_b64 s[30:31], s[30:31], 10
	v_lshl_add_u64 v[162:163], v[122:123], 0, s[30:31]
	global_load_dwordx4 v[96:99], v[162:163], off
	v_readfirstlane_b32 s30, v34
	s_ashr_i32 s31, s30, 31
	s_lshl_b64 s[30:31], s[30:31], 10
	v_lshl_add_u64 v[162:163], v[122:123], 0, s[30:31]
	global_load_dwordx4 v[100:103], v[162:163], off
	v_readfirstlane_b32 s30, v36
	s_ashr_i32 s31, s30, 31
	s_lshl_b64 s[30:31], s[30:31], 10
	v_lshl_add_u64 v[162:163], v[122:123], 0, s[30:31]
	global_load_dwordx4 v[104:107], v[162:163], off
	v_readfirstlane_b32 s30, v38
	s_ashr_i32 s31, s30, 31
	s_lshl_b64 s[30:31], s[30:31], 10
	v_lshl_add_u64 v[162:163], v[122:123], 0, s[30:31]
	global_load_dwordx4 v[108:111], v[162:163], off
	v_readfirstlane_b32 s30, v40
	s_ashr_i32 s31, s30, 31
	s_lshl_b64 s[30:31], s[30:31], 10
	v_lshl_add_u64 v[162:163], v[122:123], 0, s[30:31]
	global_load_dwordx4 v[112:115], v[162:163], off
	v_readfirstlane_b32 s30, v42
	s_ashr_i32 s31, s30, 31
	s_lshl_b64 s[30:31], s[30:31], 10
	v_lshl_add_u64 v[162:163], v[122:123], 0, s[30:31]
	global_load_dwordx4 v[180:183], v[162:163], off
	v_readfirstlane_b32 s30, v44
	s_ashr_i32 s31, s30, 31
	s_lshl_b64 s[30:31], s[30:31], 10
	v_lshl_add_u64 v[162:163], v[122:123], 0, s[30:31]
	global_load_dwordx4 v[184:187], v[162:163], off
	v_readfirstlane_b32 s30, v46
	s_ashr_i32 s31, s30, 31
	s_lshl_b64 s[30:31], s[30:31], 10
	v_lshl_add_u64 v[162:163], v[122:123], 0, s[30:31]
	global_load_dwordx4 v[188:191], v[162:163], off
	v_readfirstlane_b32 s30, v48
	s_ashr_i32 s31, s30, 31
	s_lshl_b64 s[30:31], s[30:31], 10
	v_lshl_add_u64 v[162:163], v[122:123], 0, s[30:31]
	global_load_dwordx4 v[192:195], v[162:163], off
	ds_read_b128 v[130:133], v164 offset:128
	ds_read_b128 v[134:137], v164 offset:144
	ds_read_b128 v[138:141], v164 offset:160
	ds_read_b128 v[142:145], v164 offset:176
	ds_read_b128 v[146:149], v164 offset:192
	ds_read_b128 v[150:153], v164 offset:208
	ds_read_b128 v[154:157], v164 offset:224
	ds_read_b128 v[158:161], v164 offset:240
	s_waitcnt lgkmcnt(0)
	s_waitcnt vmcnt(15)
	v_cvt_pk_f32_fp8_e32 v[196:197], v68
	v_cvt_pk_f32_fp8_sdwa v[198:199], v68 src0_sel:WORD_1
	v_cvt_pk_f32_fp8_e32 v[200:201], v69
	v_cvt_pk_f32_fp8_sdwa v[202:203], v69 src0_sel:WORD_1
	v_cvt_pk_f32_fp8_e32 v[216:217], v70
	v_cvt_pk_f32_fp8_sdwa v[218:219], v70 src0_sel:WORD_1
	v_cvt_pk_f32_fp8_e32 v[220:221], v71
	v_cvt_pk_f32_fp8_sdwa v[222:223], v71 src0_sel:WORD_1
	v_pk_fma_f32 v[6:7], v[18:19], v[196:197], v[6:7] op_sel:[1,0,0]
	v_pk_fma_f32 v[8:9], v[18:19], v[198:199], v[8:9] op_sel:[1,0,0]
	v_pk_fma_f32 v[10:11], v[18:19], v[200:201], v[10:11] op_sel:[1,0,0]
	v_pk_fma_f32 v[12:13], v[18:19], v[202:203], v[12:13] op_sel:[1,0,0]
	v_pk_fma_f32 v[14:15], v[18:19], v[216:217], v[14:15] op_sel:[1,0,0]
	v_pk_fma_f32 v[16:17], v[18:19], v[218:219], v[16:17] op_sel:[1,0,0]
	v_pk_fma_f32 v[2:3], v[18:19], v[220:221], v[2:3] op_sel:[1,0,0]
	v_pk_fma_f32 v[4:5], v[18:19], v[222:223], v[4:5] op_sel:[1,0,0]
	v_readfirstlane_b32 s30, v130
	s_ashr_i32 s31, s30, 31
	s_lshl_b64 s[30:31], s[30:31], 10
	v_lshl_add_u64 v[162:163], v[122:123], 0, s[30:31]
	global_load_dwordx4 v[68:71], v[162:163], off
	s_waitcnt vmcnt(15)
	v_cvt_pk_f32_fp8_e32 v[196:197], v72
	v_cvt_pk_f32_fp8_sdwa v[198:199], v72 src0_sel:WORD_1
	v_cvt_pk_f32_fp8_e32 v[200:201], v73
	v_cvt_pk_f32_fp8_sdwa v[202:203], v73 src0_sel:WORD_1
	v_cvt_pk_f32_fp8_e32 v[216:217], v74
	v_cvt_pk_f32_fp8_sdwa v[218:219], v74 src0_sel:WORD_1
	v_cvt_pk_f32_fp8_e32 v[220:221], v75
	v_cvt_pk_f32_fp8_sdwa v[222:223], v75 src0_sel:WORD_1
	v_pk_fma_f32 v[6:7], v[20:21], v[196:197], v[6:7] op_sel:[1,0,0]
	v_pk_fma_f32 v[8:9], v[20:21], v[198:199], v[8:9] op_sel:[1,0,0]
	v_pk_fma_f32 v[10:11], v[20:21], v[200:201], v[10:11] op_sel:[1,0,0]
	v_pk_fma_f32 v[12:13], v[20:21], v[202:203], v[12:13] op_sel:[1,0,0]
	v_pk_fma_f32 v[14:15], v[20:21], v[216:217], v[14:15] op_sel:[1,0,0]
	v_pk_fma_f32 v[16:17], v[20:21], v[218:219], v[16:17] op_sel:[1,0,0]
	v_pk_fma_f32 v[2:3], v[20:21], v[220:221], v[2:3] op_sel:[1,0,0]
	v_pk_fma_f32 v[4:5], v[20:21], v[222:223], v[4:5] op_sel:[1,0,0]
	v_readfirstlane_b32 s30, v132
	s_ashr_i32 s31, s30, 31
	s_lshl_b64 s[30:31], s[30:31], 10
	v_lshl_add_u64 v[162:163], v[122:123], 0, s[30:31]
	global_load_dwordx4 v[72:75], v[162:163], off
	s_waitcnt vmcnt(15)
;     ...
;     for (int j0 = 0; j0 < NTL * 16; j0 += 16) {
;         u32x4_t w[16]; float cj[16];
; #pragma unroll
;         for (int jj = 0; jj < 16; ++jj) { const u32x2_t pr = pl[j0 + jj]; const int ej = __builtin_amdgcn_readfirstlane((int)pr.x); cj[jj] = __uint_as_float(pr.y);
;             w[jj] = *(const u32x4_t*)(v8 + (size_t)ej * D + 16 * lane); }
; #pragma unroll
;         for (int jj = 0; jj < 16; ++jj) { const float c = cj[jj];
; #pragma unroll
;             for (int q = 0; q < 4; ++q) { const f32x2_t lo = __builtin_amdgcn_cvt_pk_f32_fp8((int)w[jj][q], false), hi = __builtin_amdgcn_cvt_pk_f32_fp8((int)w[jj][q], true);
;                 o[4 * q] += c * lo[0]; o[4 * q + 1] += c * lo[1]; o[4 * q + 2] += c * hi[0]; o[4 * q + 3] += c * hi[1]; } }
	v_cvt_pk_f32_fp8_e32 v[196:197], v76
	v_cvt_pk_f32_fp8_sdwa v[198:199], v76 src0_sel:WORD_1
	v_cvt_pk_f32_fp8_e32 v[200:201], v77
	v_cvt_pk_f32_fp8_sdwa v[202:203], v77 src0_sel:WORD_1
	v_cvt_pk_f32_fp8_e32 v[216:217], v78
	v_cvt_pk_f32_fp8_sdwa v[218:219], v78 src0_sel:WORD_1
	v_cvt_pk_f32_fp8_e32 v[220:221], v79
	v_cvt_pk_f32_fp8_sdwa v[222:223], v79 src0_sel:WORD_1
	v_pk_fma_f32 v[6:7], v[22:23], v[196:197], v[6:7] op_sel:[1,0,0]
	v_pk_fma_f32 v[8:9], v[22:23], v[198:199], v[8:9] op_sel:[1,0,0]
	v_pk_fma_f32 v[10:11], v[22:23], v[200:201], v[10:11] op_sel:[1,0,0]
	v_pk_fma_f32 v[12:13], v[22:23], v[202:203], v[12:13] op_sel:[1,0,0]
	v_pk_fma_f32 v[14:15], v[22:23], v[216:217], v[14:15] op_sel:[1,0,0]
	v_pk_fma_f32 v[16:17], v[22:23], v[218:219], v[16:17] op_sel:[1,0,0]
	v_pk_fma_f32 v[2:3], v[22:23], v[220:221], v[2:3] op_sel:[1,0,0]
	v_pk_fma_f32 v[4:5], v[22:23], v[222:223], v[4:5] op_sel:[1,0,0]
	v_readfirstlane_b32 s30, v134
	s_ashr_i32 s31, s30, 31
	s_lshl_b64 s[30:31], s[30:31], 10
	v_lshl_add_u64 v[162:163], v[122:123], 0, s[30:31]
	global_load_dwordx4 v[76:79], v[162:163], off
	s_waitcnt vmcnt(15)
	v_cvt_pk_f32_fp8_e32 v[196:197], v80
	v_cvt_pk_f32_fp8_sdwa v[198:199], v80 src0_sel:WORD_1
	v_cvt_pk_f32_fp8_e32 v[200:201], v81
	v_cvt_pk_f32_fp8_sdwa v[202:203], v81 src0_sel:WORD_1
	v_cvt_pk_f32_fp8_e32 v[216:217], v82
	v_cvt_pk_f32_fp8_sdwa v[218:219], v82 src0_sel:WORD_1
	v_cvt_pk_f32_fp8_e32 v[220:221], v83
	v_cvt_pk_f32_fp8_sdwa v[222:223], v83 src0_sel:WORD_1
	v_pk_fma_f32 v[6:7], v[24:25], v[196:197], v[6:7] op_sel:[1,0,0]
	v_pk_fma_f32 v[8:9], v[24:25], v[198:199], v[8:9] op_sel:[1,0,0]
	v_pk_fma_f32 v[10:11], v[24:25], v[200:201], v[10:11] op_sel:[1,0,0]
	v_pk_fma_f32 v[12:13], v[24:25], v[202:203], v[12:13] op_sel:[1,0,0]
	v_pk_fma_f32 v[14:15], v[24:25], v[216:217], v[14:15] op_sel:[1,0,0]
	v_pk_fma_f32 v[16:17], v[24:25], v[218:219], v[16:17] op_sel:[1,0,0]
	v_pk_fma_f32 v[2:3], v[24:25], v[220:221], v[2:3] op_sel:[1,0,0]
	v_pk_fma_f32 v[4:5], v[24:25], v[222:223], v[4:5] op_sel:[1,0,0]
	v_readfirstlane_b32 s30, v136
	s_ashr_i32 s31, s30, 31
	s_lshl_b64 s[30:31], s[30:31], 10
	v_lshl_add_u64 v[162:163], v[122:123], 0, s[30:31]
	global_load_dwordx4 v[80:83], v[162:163], off
	s_waitcnt vmcnt(15)
	v_cvt_pk_f32_fp8_e32 v[196:197], v84
	v_cvt_pk_f32_fp8_sdwa v[198:199], v84 src0_sel:WORD_1
	v_cvt_pk_f32_fp8_e32 v[200:201], v85
	v_cvt_pk_f32_fp8_sdwa v[202:203], v85 src0_sel:WORD_1
	v_cvt_pk_f32_fp8_e32 v[216:217], v86
	v_cvt_pk_f32_fp8_sdwa v[218:219], v86 src0_sel:WORD_1
	v_cvt_pk_f32_fp8_e32 v[220:221], v87
	v_cvt_pk_f32_fp8_sdwa v[222:223], v87 src0_sel:WORD_1
	v_pk_fma_f32 v[6:7], v[26:27], v[196:197], v[6:7] op_sel:[1,0,0]
	v_pk_fma_f32 v[8:9], v[26:27], v[198:199], v[8:9] op_sel:[1,0,0]
	v_pk_fma_f32 v[10:11], v[26:27], v[200:201], v[10:11] op_sel:[1,0,0]
	v_pk_fma_f32 v[12:13], v[26:27], v[202:203], v[12:13] op_sel:[1,0,0]
	v_pk_fma_f32 v[14:15], v[26:27], v[216:217], v[14:15] op_sel:[1,0,0]
	v_pk_fma_f32 v[16:17], v[26:27], v[218:219], v[16:17] op_sel:[1,0,0]
	v_pk_fma_f32 v[2:3], v[26:27], v[220:221], v[2:3] op_sel:[1,0,0]
	v_pk_fma_f32 v[4:5], v[26:27], v[222:223], v[4:5] op_sel:[1,0,0]
	v_readfirstlane_b32 s30, v138
	s_ashr_i32 s31, s30, 31
	s_lshl_b64 s[30:31], s[30:31], 10
	v_lshl_add_u64 v[162:163], v[122:123], 0, s[30:31]
	global_load_dwordx4 v[84:87], v[162:163], off
	s_waitcnt vmcnt(15)
	v_cvt_pk_f32_fp8_e32 v[196:197], v88
	v_cvt_pk_f32_fp8_sdwa v[198:199], v88 src0_sel:WORD_1
	v_cvt_pk_f32_fp8_e32 v[200:201], v89
	v_cvt_pk_f32_fp8_sdwa v[202:203], v89 src0_sel:WORD_1
	v_cvt_pk_f32_fp8_e32 v[216:217], v90
	v_cvt_pk_f32_fp8_sdwa v[218:219], v90 src0_sel:WORD_1
	v_cvt_pk_f32_fp8_e32 v[220:221], v91
	v_cvt_pk_f32_fp8_sdwa v[222:223], v91 src0_sel:WORD_1
	v_pk_fma_f32 v[6:7], v[28:29], v[196:197], v[6:7] op_sel:[1,0,0]
	v_pk_fma_f32 v[8:9], v[28:29], v[198:199], v[8:9] op_sel:[1,0,0]
	v_pk_fma_f32 v[10:11], v[28:29], v[200:201], v[10:11] op_sel:[1,0,0]
	v_pk_fma_f32 v[12:13], v[28:29], v[202:203], v[12:13] op_sel:[1,0,0]
	v_pk_fma_f32 v[14:15], v[28:29], v[216:217], v[14:15] op_sel:[1,0,0]
	v_pk_fma_f32 v[16:17], v[28:29], v[218:219], v[16:17] op_sel:[1,0,0]
	v_pk_fma_f32 v[2:3], v[28:29], v[220:221], v[2:3] op_sel:[1,0,0]
	v_pk_fma_f32 v[4:5], v[28:29], v[222:223], v[4:5] op_sel:[1,0,0]
	v_readfirstlane_b32 s30, v140
	s_ashr_i32 s31, s30, 31
	s_lshl_b64 s[30:31], s[30:31], 10
	v_lshl_add_u64 v[162:163], v[122:123], 0, s[30:31]
	global_load_dwordx4 v[88:91], v[162:163], off
	s_waitcnt vmcnt(15)
	v_cvt_pk_f32_fp8_e32 v[196:197], v92
	v_cvt_pk_f32_fp8_sdwa v[198:199], v92 src0_sel:WORD_1
	v_cvt_pk_f32_fp8_e32 v[200:201], v93
	v_cvt_pk_f32_fp8_sdwa v[202:203], v93 src0_sel:WORD_1
	v_cvt_pk_f32_fp8_e32 v[216:217], v94
	v_cvt_pk_f32_fp8_sdwa v[218:219], v94 src0_sel:WORD_1
	v_cvt_pk_f32_fp8_e32 v[220:221], v95
	v_cvt_pk_f32_fp8_sdwa v[222:223], v95 src0_sel:WORD_1
	v_pk_fma_f32 v[6:7], v[30:31], v[196:197], v[6:7] op_sel:[1,0,0]
	v_pk_fma_f32 v[8:9], v[30:31], v[198:199], v[8:9] op_sel:[1,0,0]
	v_pk_fma_f32 v[10:11], v[30:31], v[200:201], v[10:11] op_sel:[1,0,0]
	v_pk_fma_f32 v[12:13], v[30:31], v[202:203], v[12:13] op_sel:[1,0,0]
	v_pk_fma_f32 v[14:15], v[30:31], v[216:217], v[14:15] op_sel:[1,0,0]
	v_pk_fma_f32 v[16:17], v[30:31], v[218:219], v[16:17] op_sel:[1,0,0]
	v_pk_fma_f32 v[2:3], v[30:31], v[220:221], v[2:3] op_sel:[1,0,0]
	v_pk_fma_f32 v[4:5], v[30:31], v[222:223], v[4:5] op_sel:[1,0,0]
	v_readfirstlane_b32 s30, v142
	s_ashr_i32 s31, s30, 31
	s_lshl_b64 s[30:31], s[30:31], 10
	v_lshl_add_u64 v[162:163], v[122:123], 0, s[30:31]
	global_load_dwordx4 v[92:95], v[162:163], off
	s_waitcnt vmcnt(15)
;     ...
;     for (int j0 = 0; j0 < NTL * 16; j0 += 16) {
;         u32x4_t w[16]; float cj[16];
; #pragma unroll
;         for (int jj = 0; jj < 16; ++jj) { const u32x2_t pr = pl[j0 + jj]; const int ej = __builtin_amdgcn_readfirstlane((int)pr.x); cj[jj] = __uint_as_float(pr.y);
;             w[jj] = *(const u32x4_t*)(v8 + (size_t)ej * D + 16 * lane); }
; #pragma unroll
;         for (int jj = 0; jj < 16; ++jj) { const float c = cj[jj];
; #pragma unroll
;             for (int q = 0; q < 4; ++q) { const f32x2_t lo = __builtin_amdgcn_cvt_pk_f32_fp8((int)w[jj][q], false), hi = __builtin_amdgcn_cvt_pk_f32_fp8((int)w[jj][q], true);
;                 o[4 * q] += c * lo[0]; o[4 * q + 1] += c * lo[1]; o[4 * q + 2] += c * hi[0]; o[4 * q + 3] += c * hi[1]; } }
	v_cvt_pk_f32_fp8_e32 v[196:197], v96
	v_cvt_pk_f32_fp8_sdwa v[198:199], v96 src0_sel:WORD_1
	v_cvt_pk_f32_fp8_e32 v[200:201], v97
	v_cvt_pk_f32_fp8_sdwa v[202:203], v97 src0_sel:WORD_1
	v_cvt_pk_f32_fp8_e32 v[216:217], v98
	v_cvt_pk_f32_fp8_sdwa v[218:219], v98 src0_sel:WORD_1
	v_cvt_pk_f32_fp8_e32 v[220:221], v99
	v_cvt_pk_f32_fp8_sdwa v[222:223], v99 src0_sel:WORD_1
	v_pk_fma_f32 v[6:7], v[32:33], v[196:197], v[6:7] op_sel:[1,0,0]
	v_pk_fma_f32 v[8:9], v[32:33], v[198:199], v[8:9] op_sel:[1,0,0]
	v_pk_fma_f32 v[10:11], v[32:33], v[200:201], v[10:11] op_sel:[1,0,0]
	v_pk_fma_f32 v[12:13], v[32:33], v[202:203], v[12:13] op_sel:[1,0,0]
	v_pk_fma_f32 v[14:15], v[32:33], v[216:217], v[14:15] op_sel:[1,0,0]
	v_pk_fma_f32 v[16:17], v[32:33], v[218:219], v[16:17] op_sel:[1,0,0]
	v_pk_fma_f32 v[2:3], v[32:33], v[220:221], v[2:3] op_sel:[1,0,0]
	v_pk_fma_f32 v[4:5], v[32:33], v[222:223], v[4:5] op_sel:[1,0,0]
	v_readfirstlane_b32 s30, v144
	s_ashr_i32 s31, s30, 31
	s_lshl_b64 s[30:31], s[30:31], 10
	v_lshl_add_u64 v[162:163], v[122:123], 0, s[30:31]
	global_load_dwordx4 v[96:99], v[162:163], off
	s_waitcnt vmcnt(15)
	v_cvt_pk_f32_fp8_e32 v[196:197], v100
	v_cvt_pk_f32_fp8_sdwa v[198:199], v100 src0_sel:WORD_1
	v_cvt_pk_f32_fp8_e32 v[200:201], v101
	v_cvt_pk_f32_fp8_sdwa v[202:203], v101 src0_sel:WORD_1
	v_cvt_pk_f32_fp8_e32 v[216:217], v102
	v_cvt_pk_f32_fp8_sdwa v[218:219], v102 src0_sel:WORD_1
	v_cvt_pk_f32_fp8_e32 v[220:221], v103
	v_cvt_pk_f32_fp8_sdwa v[222:223], v103 src0_sel:WORD_1
	v_pk_fma_f32 v[6:7], v[34:35], v[196:197], v[6:7] op_sel:[1,0,0]
	v_pk_fma_f32 v[8:9], v[34:35], v[198:199], v[8:9] op_sel:[1,0,0]
	v_pk_fma_f32 v[10:11], v[34:35], v[200:201], v[10:11] op_sel:[1,0,0]
	v_pk_fma_f32 v[12:13], v[34:35], v[202:203], v[12:13] op_sel:[1,0,0]
	v_pk_fma_f32 v[14:15], v[34:35], v[216:217], v[14:15] op_sel:[1,0,0]
	v_pk_fma_f32 v[16:17], v[34:35], v[218:219], v[16:17] op_sel:[1,0,0]
	v_pk_fma_f32 v[2:3], v[34:35], v[220:221], v[2:3] op_sel:[1,0,0]
	v_pk_fma_f32 v[4:5], v[34:35], v[222:223], v[4:5] op_sel:[1,0,0]
	v_readfirstlane_b32 s30, v146
	s_ashr_i32 s31, s30, 31
	s_lshl_b64 s[30:31], s[30:31], 10
	v_lshl_add_u64 v[162:163], v[122:123], 0, s[30:31]
	global_load_dwordx4 v[100:103], v[162:163], off
	s_waitcnt vmcnt(15)
	v_cvt_pk_f32_fp8_e32 v[196:197], v104
	v_cvt_pk_f32_fp8_sdwa v[198:199], v104 src0_sel:WORD_1
	v_cvt_pk_f32_fp8_e32 v[200:201], v105
	v_cvt_pk_f32_fp8_sdwa v[202:203], v105 src0_sel:WORD_1
	v_cvt_pk_f32_fp8_e32 v[216:217], v106
	v_cvt_pk_f32_fp8_sdwa v[218:219], v106 src0_sel:WORD_1
	v_cvt_pk_f32_fp8_e32 v[220:221], v107
	v_cvt_pk_f32_fp8_sdwa v[222:223], v107 src0_sel:WORD_1
	v_pk_fma_f32 v[6:7], v[36:37], v[196:197], v[6:7] op_sel:[1,0,0]
	v_pk_fma_f32 v[8:9], v[36:37], v[198:199], v[8:9] op_sel:[1,0,0]
	v_pk_fma_f32 v[10:11], v[36:37], v[200:201], v[10:11] op_sel:[1,0,0]
	v_pk_fma_f32 v[12:13], v[36:37], v[202:203], v[12:13] op_sel:[1,0,0]
	v_pk_fma_f32 v[14:15], v[36:37], v[216:217], v[14:15] op_sel:[1,0,0]
	v_pk_fma_f32 v[16:17], v[36:37], v[218:219], v[16:17] op_sel:[1,0,0]
	v_pk_fma_f32 v[2:3], v[36:37], v[220:221], v[2:3] op_sel:[1,0,0]
	v_pk_fma_f32 v[4:5], v[36:37], v[222:223], v[4:5] op_sel:[1,0,0]
	v_readfirstlane_b32 s30, v148
	s_ashr_i32 s31, s30, 31
	s_lshl_b64 s[30:31], s[30:31], 10
	v_lshl_add_u64 v[162:163], v[122:123], 0, s[30:31]
	global_load_dwordx4 v[104:107], v[162:163], off
	s_waitcnt vmcnt(15)
	v_cvt_pk_f32_fp8_e32 v[196:197], v108
	v_cvt_pk_f32_fp8_sdwa v[198:199], v108 src0_sel:WORD_1
	v_cvt_pk_f32_fp8_e32 v[200:201], v109
	v_cvt_pk_f32_fp8_sdwa v[202:203], v109 src0_sel:WORD_1
	v_cvt_pk_f32_fp8_e32 v[216:217], v110
	v_cvt_pk_f32_fp8_sdwa v[218:219], v110 src0_sel:WORD_1
	v_cvt_pk_f32_fp8_e32 v[220:221], v111
	v_cvt_pk_f32_fp8_sdwa v[222:223], v111 src0_sel:WORD_1
	v_pk_fma_f32 v[6:7], v[38:39], v[196:197], v[6:7] op_sel:[1,0,0]
	v_pk_fma_f32 v[8:9], v[38:39], v[198:199], v[8:9] op_sel:[1,0,0]
	v_pk_fma_f32 v[10:11], v[38:39], v[200:201], v[10:11] op_sel:[1,0,0]
	v_pk_fma_f32 v[12:13], v[38:39], v[202:203], v[12:13] op_sel:[1,0,0]
	v_pk_fma_f32 v[14:15], v[38:39], v[216:217], v[14:15] op_sel:[1,0,0]
	v_pk_fma_f32 v[16:17], v[38:39], v[218:219], v[16:17] op_sel:[1,0,0]
	v_pk_fma_f32 v[2:3], v[38:39], v[220:221], v[2:3] op_sel:[1,0,0]
	v_pk_fma_f32 v[4:5], v[38:39], v[222:223], v[4:5] op_sel:[1,0,0]
	v_readfirstlane_b32 s30, v150
	s_ashr_i32 s31, s30, 31
	s_lshl_b64 s[30:31], s[30:31], 10
	v_lshl_add_u64 v[162:163], v[122:123], 0, s[30:31]
	global_load_dwordx4 v[108:111], v[162:163], off
	s_waitcnt vmcnt(15)
	v_cvt_pk_f32_fp8_e32 v[196:197], v112
	v_cvt_pk_f32_fp8_sdwa v[198:199], v112 src0_sel:WORD_1
	v_cvt_pk_f32_fp8_e32 v[200:201], v113
	v_cvt_pk_f32_fp8_sdwa v[202:203], v113 src0_sel:WORD_1
	v_cvt_pk_f32_fp8_e32 v[216:217], v114
	v_cvt_pk_f32_fp8_sdwa v[218:219], v114 src0_sel:WORD_1
	v_cvt_pk_f32_fp8_e32 v[220:221], v115
	v_cvt_pk_f32_fp8_sdwa v[222:223], v115 src0_sel:WORD_1
	v_pk_fma_f32 v[6:7], v[40:41], v[196:197], v[6:7] op_sel:[1,0,0]
	v_pk_fma_f32 v[8:9], v[40:41], v[198:199], v[8:9] op_sel:[1,0,0]
	v_pk_fma_f32 v[10:11], v[40:41], v[200:201], v[10:11] op_sel:[1,0,0]
	v_pk_fma_f32 v[12:13], v[40:41], v[202:203], v[12:13] op_sel:[1,0,0]
	v_pk_fma_f32 v[14:15], v[40:41], v[216:217], v[14:15] op_sel:[1,0,0]
	v_pk_fma_f32 v[16:17], v[40:41], v[218:219], v[16:17] op_sel:[1,0,0]
	v_pk_fma_f32 v[2:3], v[40:41], v[220:221], v[2:3] op_sel:[1,0,0]
	v_pk_fma_f32 v[4:5], v[40:41], v[222:223], v[4:5] op_sel:[1,0,0]
	v_readfirstlane_b32 s30, v152
	s_ashr_i32 s31, s30, 31
	s_lshl_b64 s[30:31], s[30:31], 10
	v_lshl_add_u64 v[162:163], v[122:123], 0, s[30:31]
	global_load_dwordx4 v[112:115], v[162:163], off
	s_waitcnt vmcnt(15)
;     ...
;     for (int j0 = 0; j0 < NTL * 16; j0 += 16) {
;         u32x4_t w[16]; float cj[16];
; #pragma unroll
;         for (int jj = 0; jj < 16; ++jj) { const u32x2_t pr = pl[j0 + jj]; const int ej = __builtin_amdgcn_readfirstlane((int)pr.x); cj[jj] = __uint_as_float(pr.y);
;             w[jj] = *(const u32x4_t*)(v8 + (size_t)ej * D + 16 * lane); }
; #pragma unroll
;         for (int jj = 0; jj < 16; ++jj) { const float c = cj[jj];
; #pragma unroll
;             for (int q = 0; q < 4; ++q) { const f32x2_t lo = __builtin_amdgcn_cvt_pk_f32_fp8((int)w[jj][q], false), hi = __builtin_amdgcn_cvt_pk_f32_fp8((int)w[jj][q], true);
;                 o[4 * q] += c * lo[0]; o[4 * q + 1] += c * lo[1]; o[4 * q + 2] += c * hi[0]; o[4 * q + 3] += c * hi[1]; } }
	v_cvt_pk_f32_fp8_e32 v[196:197], v180
	v_cvt_pk_f32_fp8_sdwa v[198:199], v180 src0_sel:WORD_1
	v_cvt_pk_f32_fp8_e32 v[200:201], v181
	v_cvt_pk_f32_fp8_sdwa v[202:203], v181 src0_sel:WORD_1
	v_cvt_pk_f32_fp8_e32 v[216:217], v182
	v_cvt_pk_f32_fp8_sdwa v[218:219], v182 src0_sel:WORD_1
	v_cvt_pk_f32_fp8_e32 v[220:221], v183
	v_cvt_pk_f32_fp8_sdwa v[222:223], v183 src0_sel:WORD_1
	v_pk_fma_f32 v[6:7], v[42:43], v[196:197], v[6:7] op_sel:[1,0,0]
	v_pk_fma_f32 v[8:9], v[42:43], v[198:199], v[8:9] op_sel:[1,0,0]
	v_pk_fma_f32 v[10:11], v[42:43], v[200:201], v[10:11] op_sel:[1,0,0]
	v_pk_fma_f32 v[12:13], v[42:43], v[202:203], v[12:13] op_sel:[1,0,0]
	v_pk_fma_f32 v[14:15], v[42:43], v[216:217], v[14:15] op_sel:[1,0,0]
	v_pk_fma_f32 v[16:17], v[42:43], v[218:219], v[16:17] op_sel:[1,0,0]
	v_pk_fma_f32 v[2:3], v[42:43], v[220:221], v[2:3] op_sel:[1,0,0]
	v_pk_fma_f32 v[4:5], v[42:43], v[222:223], v[4:5] op_sel:[1,0,0]
	v_readfirstlane_b32 s30, v154
	s_ashr_i32 s31, s30, 31
	s_lshl_b64 s[30:31], s[30:31], 10
	v_lshl_add_u64 v[162:163], v[122:123], 0, s[30:31]
	global_load_dwordx4 v[180:183], v[162:163], off
	s_waitcnt vmcnt(15)
	v_cvt_pk_f32_fp8_e32 v[196:197], v184
	v_cvt_pk_f32_fp8_sdwa v[198:199], v184 src0_sel:WORD_1
	v_cvt_pk_f32_fp8_e32 v[200:201], v185
	v_cvt_pk_f32_fp8_sdwa v[202:203], v185 src0_sel:WORD_1
	v_cvt_pk_f32_fp8_e32 v[216:217], v186
	v_cvt_pk_f32_fp8_sdwa v[218:219], v186 src0_sel:WORD_1
	v_cvt_pk_f32_fp8_e32 v[220:221], v187
	v_cvt_pk_f32_fp8_sdwa v[222:223], v187 src0_sel:WORD_1
	v_pk_fma_f32 v[6:7], v[44:45], v[196:197], v[6:7] op_sel:[1,0,0]
	v_pk_fma_f32 v[8:9], v[44:45], v[198:199], v[8:9] op_sel:[1,0,0]
	v_pk_fma_f32 v[10:11], v[44:45], v[200:201], v[10:11] op_sel:[1,0,0]
	v_pk_fma_f32 v[12:13], v[44:45], v[202:203], v[12:13] op_sel:[1,0,0]
	v_pk_fma_f32 v[14:15], v[44:45], v[216:217], v[14:15] op_sel:[1,0,0]
	v_pk_fma_f32 v[16:17], v[44:45], v[218:219], v[16:17] op_sel:[1,0,0]
	v_pk_fma_f32 v[2:3], v[44:45], v[220:221], v[2:3] op_sel:[1,0,0]
	v_pk_fma_f32 v[4:5], v[44:45], v[222:223], v[4:5] op_sel:[1,0,0]
	v_readfirstlane_b32 s30, v156
	s_ashr_i32 s31, s30, 31
	s_lshl_b64 s[30:31], s[30:31], 10
	v_lshl_add_u64 v[162:163], v[122:123], 0, s[30:31]
	global_load_dwordx4 v[184:187], v[162:163], off
	s_waitcnt vmcnt(15)
	v_cvt_pk_f32_fp8_e32 v[196:197], v188
	v_cvt_pk_f32_fp8_sdwa v[198:199], v188 src0_sel:WORD_1
	v_cvt_pk_f32_fp8_e32 v[200:201], v189
	v_cvt_pk_f32_fp8_sdwa v[202:203], v189 src0_sel:WORD_1
	v_cvt_pk_f32_fp8_e32 v[216:217], v190
	v_cvt_pk_f32_fp8_sdwa v[218:219], v190 src0_sel:WORD_1
	v_cvt_pk_f32_fp8_e32 v[220:221], v191
	v_cvt_pk_f32_fp8_sdwa v[222:223], v191 src0_sel:WORD_1
	v_pk_fma_f32 v[6:7], v[46:47], v[196:197], v[6:7] op_sel:[1,0,0]
	v_pk_fma_f32 v[8:9], v[46:47], v[198:199], v[8:9] op_sel:[1,0,0]
	v_pk_fma_f32 v[10:11], v[46:47], v[200:201], v[10:11] op_sel:[1,0,0]
	v_pk_fma_f32 v[12:13], v[46:47], v[202:203], v[12:13] op_sel:[1,0,0]
	v_pk_fma_f32 v[14:15], v[46:47], v[216:217], v[14:15] op_sel:[1,0,0]
	v_pk_fma_f32 v[16:17], v[46:47], v[218:219], v[16:17] op_sel:[1,0,0]
	v_pk_fma_f32 v[2:3], v[46:47], v[220:221], v[2:3] op_sel:[1,0,0]
	v_pk_fma_f32 v[4:5], v[46:47], v[222:223], v[4:5] op_sel:[1,0,0]
	v_readfirstlane_b32 s30, v158
	s_ashr_i32 s31, s30, 31
	s_lshl_b64 s[30:31], s[30:31], 10
	v_lshl_add_u64 v[162:163], v[122:123], 0, s[30:31]
	global_load_dwordx4 v[188:191], v[162:163], off
	s_waitcnt vmcnt(15)
	v_cvt_pk_f32_fp8_e32 v[196:197], v192
	v_cvt_pk_f32_fp8_sdwa v[198:199], v192 src0_sel:WORD_1
	v_cvt_pk_f32_fp8_e32 v[200:201], v193
	v_cvt_pk_f32_fp8_sdwa v[202:203], v193 src0_sel:WORD_1
	v_cvt_pk_f32_fp8_e32 v[216:217], v194
	v_cvt_pk_f32_fp8_sdwa v[218:219], v194 src0_sel:WORD_1
	v_cvt_pk_f32_fp8_e32 v[220:221], v195
	v_cvt_pk_f32_fp8_sdwa v[222:223], v195 src0_sel:WORD_1
	v_pk_fma_f32 v[6:7], v[48:49], v[196:197], v[6:7] op_sel:[1,0,0]
	v_pk_fma_f32 v[8:9], v[48:49], v[198:199], v[8:9] op_sel:[1,0,0]
	v_pk_fma_f32 v[10:11], v[48:49], v[200:201], v[10:11] op_sel:[1,0,0]
	v_pk_fma_f32 v[12:13], v[48:49], v[202:203], v[12:13] op_sel:[1,0,0]
	v_pk_fma_f32 v[14:15], v[48:49], v[216:217], v[14:15] op_sel:[1,0,0]
	v_pk_fma_f32 v[16:17], v[48:49], v[218:219], v[16:17] op_sel:[1,0,0]
	v_pk_fma_f32 v[2:3], v[48:49], v[220:221], v[2:3] op_sel:[1,0,0]
	v_pk_fma_f32 v[4:5], v[48:49], v[222:223], v[4:5] op_sel:[1,0,0]
	v_readfirstlane_b32 s30, v160
	s_ashr_i32 s31, s30, 31
	s_lshl_b64 s[30:31], s[30:31], 10
	v_lshl_add_u64 v[162:163], v[122:123], 0, s[30:31]
	global_load_dwordx4 v[192:195], v[162:163], off
	ds_read_b128 v[18:21], v164 offset:256
	ds_read_b128 v[22:25], v164 offset:272
	ds_read_b128 v[26:29], v164 offset:288
	ds_read_b128 v[30:33], v164 offset:304
	ds_read_b128 v[34:37], v164 offset:320
	ds_read_b128 v[38:41], v164 offset:336
	ds_read_b128 v[42:45], v164 offset:352
	ds_read_b128 v[46:49], v164 offset:368
	s_waitcnt lgkmcnt(0)
	s_waitcnt vmcnt(15)
	v_cvt_pk_f32_fp8_e32 v[196:197], v68
	v_cvt_pk_f32_fp8_sdwa v[198:199], v68 src0_sel:WORD_1
	v_cvt_pk_f32_fp8_e32 v[200:201], v69
	v_cvt_pk_f32_fp8_sdwa v[202:203], v69 src0_sel:WORD_1
	v_cvt_pk_f32_fp8_e32 v[216:217], v70
	v_cvt_pk_f32_fp8_sdwa v[218:219], v70 src0_sel:WORD_1
	v_cvt_pk_f32_fp8_e32 v[220:221], v71
	v_cvt_pk_f32_fp8_sdwa v[222:223], v71 src0_sel:WORD_1
	v_pk_fma_f32 v[6:7], v[130:131], v[196:197], v[6:7] op_sel:[1,0,0]
	v_pk_fma_f32 v[8:9], v[130:131], v[198:199], v[8:9] op_sel:[1,0,0]
	v_pk_fma_f32 v[10:11], v[130:131], v[200:201], v[10:11] op_sel:[1,0,0]
	v_pk_fma_f32 v[12:13], v[130:131], v[202:203], v[12:13] op_sel:[1,0,0]
	v_pk_fma_f32 v[14:15], v[130:131], v[216:217], v[14:15] op_sel:[1,0,0]
	v_pk_fma_f32 v[16:17], v[130:131], v[218:219], v[16:17] op_sel:[1,0,0]
	v_pk_fma_f32 v[2:3], v[130:131], v[220:221], v[2:3] op_sel:[1,0,0]
	v_pk_fma_f32 v[4:5], v[130:131], v[222:223], v[4:5] op_sel:[1,0,0]
	v_readfirstlane_b32 s30, v18
	s_ashr_i32 s31, s30, 31
	s_lshl_b64 s[30:31], s[30:31], 10
	v_lshl_add_u64 v[162:163], v[122:123], 0, s[30:31]
	global_load_dwordx4 v[68:71], v[162:163], off
	s_waitcnt vmcnt(15)
;     ...
;     for (int j0 = 0; j0 < NTL * 16; j0 += 16) {
;         u32x4_t w[16]; float cj[16];
; #pragma unroll
;         for (int jj = 0; jj < 16; ++jj) { const u32x2_t pr = pl[j0 + jj]; const int ej = __builtin_amdgcn_readfirstlane((int)pr.x); cj[jj] = __uint_as_float(pr.y);
;             w[jj] = *(const u32x4_t*)(v8 + (size_t)ej * D + 16 * lane); }
; #pragma unroll
;         for (int jj = 0; jj < 16; ++jj) { const float c = cj[jj];
; #pragma unroll
;             for (int q = 0; q < 4; ++q) { const f32x2_t lo = __builtin_amdgcn_cvt_pk_f32_fp8((int)w[jj][q], false), hi = __builtin_amdgcn_cvt_pk_f32_fp8((int)w[jj][q], true);
;                 o[4 * q] += c * lo[0]; o[4 * q + 1] += c * lo[1]; o[4 * q + 2] += c * hi[0]; o[4 * q + 3] += c * hi[1]; } }
	v_cvt_pk_f32_fp8_e32 v[196:197], v72
	v_cvt_pk_f32_fp8_sdwa v[198:199], v72 src0_sel:WORD_1
	v_cvt_pk_f32_fp8_e32 v[200:201], v73
	v_cvt_pk_f32_fp8_sdwa v[202:203], v73 src0_sel:WORD_1
	v_cvt_pk_f32_fp8_e32 v[216:217], v74
	v_cvt_pk_f32_fp8_sdwa v[218:219], v74 src0_sel:WORD_1
	v_cvt_pk_f32_fp8_e32 v[220:221], v75
	v_cvt_pk_f32_fp8_sdwa v[222:223], v75 src0_sel:WORD_1
	v_pk_fma_f32 v[6:7], v[132:133], v[196:197], v[6:7] op_sel:[1,0,0]
	v_pk_fma_f32 v[8:9], v[132:133], v[198:199], v[8:9] op_sel:[1,0,0]
	v_pk_fma_f32 v[10:11], v[132:133], v[200:201], v[10:11] op_sel:[1,0,0]
	v_pk_fma_f32 v[12:13], v[132:133], v[202:203], v[12:13] op_sel:[1,0,0]
	v_pk_fma_f32 v[14:15], v[132:133], v[216:217], v[14:15] op_sel:[1,0,0]
	v_pk_fma_f32 v[16:17], v[132:133], v[218:219], v[16:17] op_sel:[1,0,0]
	v_pk_fma_f32 v[2:3], v[132:133], v[220:221], v[2:3] op_sel:[1,0,0]
	v_pk_fma_f32 v[4:5], v[132:133], v[222:223], v[4:5] op_sel:[1,0,0]
	v_readfirstlane_b32 s30, v20
	s_ashr_i32 s31, s30, 31
	s_lshl_b64 s[30:31], s[30:31], 10
	v_lshl_add_u64 v[162:163], v[122:123], 0, s[30:31]
	global_load_dwordx4 v[72:75], v[162:163], off
	s_waitcnt vmcnt(15)
	v_cvt_pk_f32_fp8_e32 v[196:197], v76
	v_cvt_pk_f32_fp8_sdwa v[198:199], v76 src0_sel:WORD_1
	v_cvt_pk_f32_fp8_e32 v[200:201], v77
	v_cvt_pk_f32_fp8_sdwa v[202:203], v77 src0_sel:WORD_1
	v_cvt_pk_f32_fp8_e32 v[216:217], v78
	v_cvt_pk_f32_fp8_sdwa v[218:219], v78 src0_sel:WORD_1
	v_cvt_pk_f32_fp8_e32 v[220:221], v79
	v_cvt_pk_f32_fp8_sdwa v[222:223], v79 src0_sel:WORD_1
	v_pk_fma_f32 v[6:7], v[134:135], v[196:197], v[6:7] op_sel:[1,0,0]
	v_pk_fma_f32 v[8:9], v[134:135], v[198:199], v[8:9] op_sel:[1,0,0]
	v_pk_fma_f32 v[10:11], v[134:135], v[200:201], v[10:11] op_sel:[1,0,0]
	v_pk_fma_f32 v[12:13], v[134:135], v[202:203], v[12:13] op_sel:[1,0,0]
	v_pk_fma_f32 v[14:15], v[134:135], v[216:217], v[14:15] op_sel:[1,0,0]
	v_pk_fma_f32 v[16:17], v[134:135], v[218:219], v[16:17] op_sel:[1,0,0]
	v_pk_fma_f32 v[2:3], v[134:135], v[220:221], v[2:3] op_sel:[1,0,0]
	v_pk_fma_f32 v[4:5], v[134:135], v[222:223], v[4:5] op_sel:[1,0,0]
	v_readfirstlane_b32 s30, v22
	s_ashr_i32 s31, s30, 31
	s_lshl_b64 s[30:31], s[30:31], 10
	v_lshl_add_u64 v[162:163], v[122:123], 0, s[30:31]
	global_load_dwordx4 v[76:79], v[162:163], off
	s_waitcnt vmcnt(15)
	v_cvt_pk_f32_fp8_e32 v[196:197], v80
	v_cvt_pk_f32_fp8_sdwa v[198:199], v80 src0_sel:WORD_1
	v_cvt_pk_f32_fp8_e32 v[200:201], v81
	v_cvt_pk_f32_fp8_sdwa v[202:203], v81 src0_sel:WORD_1
	v_cvt_pk_f32_fp8_e32 v[216:217], v82
	v_cvt_pk_f32_fp8_sdwa v[218:219], v82 src0_sel:WORD_1
	v_cvt_pk_f32_fp8_e32 v[220:221], v83
	v_cvt_pk_f32_fp8_sdwa v[222:223], v83 src0_sel:WORD_1
	v_pk_fma_f32 v[6:7], v[136:137], v[196:197], v[6:7] op_sel:[1,0,0]
	v_pk_fma_f32 v[8:9], v[136:137], v[198:199], v[8:9] op_sel:[1,0,0]
	v_pk_fma_f32 v[10:11], v[136:137], v[200:201], v[10:11] op_sel:[1,0,0]
	v_pk_fma_f32 v[12:13], v[136:137], v[202:203], v[12:13] op_sel:[1,0,0]
	v_pk_fma_f32 v[14:15], v[136:137], v[216:217], v[14:15] op_sel:[1,0,0]
	v_pk_fma_f32 v[16:17], v[136:137], v[218:219], v[16:17] op_sel:[1,0,0]
	v_pk_fma_f32 v[2:3], v[136:137], v[220:221], v[2:3] op_sel:[1,0,0]
	v_pk_fma_f32 v[4:5], v[136:137], v[222:223], v[4:5] op_sel:[1,0,0]
	v_readfirstlane_b32 s30, v24
	s_ashr_i32 s31, s30, 31
	s_lshl_b64 s[30:31], s[30:31], 10
	v_lshl_add_u64 v[162:163], v[122:123], 0, s[30:31]
	global_load_dwordx4 v[80:83], v[162:163], off
	s_waitcnt vmcnt(15)
	v_cvt_pk_f32_fp8_e32 v[196:197], v84
	v_cvt_pk_f32_fp8_sdwa v[198:199], v84 src0_sel:WORD_1
	v_cvt_pk_f32_fp8_e32 v[200:201], v85
	v_cvt_pk_f32_fp8_sdwa v[202:203], v85 src0_sel:WORD_1
	v_cvt_pk_f32_fp8_e32 v[216:217], v86
	v_cvt_pk_f32_fp8_sdwa v[218:219], v86 src0_sel:WORD_1
	v_cvt_pk_f32_fp8_e32 v[220:221], v87
	v_cvt_pk_f32_fp8_sdwa v[222:223], v87 src0_sel:WORD_1
	v_pk_fma_f32 v[6:7], v[138:139], v[196:197], v[6:7] op_sel:[1,0,0]
	v_pk_fma_f32 v[8:9], v[138:139], v[198:199], v[8:9] op_sel:[1,0,0]
	v_pk_fma_f32 v[10:11], v[138:139], v[200:201], v[10:11] op_sel:[1,0,0]
	v_pk_fma_f32 v[12:13], v[138:139], v[202:203], v[12:13] op_sel:[1,0,0]
	v_pk_fma_f32 v[14:15], v[138:139], v[216:217], v[14:15] op_sel:[1,0,0]
	v_pk_fma_f32 v[16:17], v[138:139], v[218:219], v[16:17] op_sel:[1,0,0]
	v_pk_fma_f32 v[2:3], v[138:139], v[220:221], v[2:3] op_sel:[1,0,0]
	v_pk_fma_f32 v[4:5], v[138:139], v[222:223], v[4:5] op_sel:[1,0,0]
	v_readfirstlane_b32 s30, v26
	s_ashr_i32 s31, s30, 31
	s_lshl_b64 s[30:31], s[30:31], 10
	v_lshl_add_u64 v[162:163], v[122:123], 0, s[30:31]
	global_load_dwordx4 v[84:87], v[162:163], off
	s_waitcnt vmcnt(15)
	v_cvt_pk_f32_fp8_e32 v[196:197], v88
	v_cvt_pk_f32_fp8_sdwa v[198:199], v88 src0_sel:WORD_1
	v_cvt_pk_f32_fp8_e32 v[200:201], v89
	v_cvt_pk_f32_fp8_sdwa v[202:203], v89 src0_sel:WORD_1
	v_cvt_pk_f32_fp8_e32 v[216:217], v90
	v_cvt_pk_f32_fp8_sdwa v[218:219], v90 src0_sel:WORD_1
	v_cvt_pk_f32_fp8_e32 v[220:221], v91
	v_cvt_pk_f32_fp8_sdwa v[222:223], v91 src0_sel:WORD_1
	v_pk_fma_f32 v[6:7], v[140:141], v[196:197], v[6:7] op_sel:[1,0,0]
	v_pk_fma_f32 v[8:9], v[140:141], v[198:199], v[8:9] op_sel:[1,0,0]
	v_pk_fma_f32 v[10:11], v[140:141], v[200:201], v[10:11] op_sel:[1,0,0]
	v_pk_fma_f32 v[12:13], v[140:141], v[202:203], v[12:13] op_sel:[1,0,0]
	v_pk_fma_f32 v[14:15], v[140:141], v[216:217], v[14:15] op_sel:[1,0,0]
	v_pk_fma_f32 v[16:17], v[140:141], v[218:219], v[16:17] op_sel:[1,0,0]
	v_pk_fma_f32 v[2:3], v[140:141], v[220:221], v[2:3] op_sel:[1,0,0]
	v_pk_fma_f32 v[4:5], v[140:141], v[222:223], v[4:5] op_sel:[1,0,0]
	v_readfirstlane_b32 s30, v28
	s_ashr_i32 s31, s30, 31
	s_lshl_b64 s[30:31], s[30:31], 10
	v_lshl_add_u64 v[162:163], v[122:123], 0, s[30:31]
	global_load_dwordx4 v[88:91], v[162:163], off
	s_waitcnt vmcnt(15)
;     ...
;     for (int j0 = 0; j0 < NTL * 16; j0 += 16) {
;         u32x4_t w[16]; float cj[16];
; #pragma unroll
;         for (int jj = 0; jj < 16; ++jj) { const u32x2_t pr = pl[j0 + jj]; const int ej = __builtin_amdgcn_readfirstlane((int)pr.x); cj[jj] = __uint_as_float(pr.y);
;             w[jj] = *(const u32x4_t*)(v8 + (size_t)ej * D + 16 * lane); }
; #pragma unroll
;         for (int jj = 0; jj < 16; ++jj) { const float c = cj[jj];
; #pragma unroll
;             for (int q = 0; q < 4; ++q) { const f32x2_t lo = __builtin_amdgcn_cvt_pk_f32_fp8((int)w[jj][q], false), hi = __builtin_amdgcn_cvt_pk_f32_fp8((int)w[jj][q], true);
;                 o[4 * q] += c * lo[0]; o[4 * q + 1] += c * lo[1]; o[4 * q + 2] += c * hi[0]; o[4 * q + 3] += c * hi[1]; } }
	v_cvt_pk_f32_fp8_e32 v[196:197], v92
	v_cvt_pk_f32_fp8_sdwa v[198:199], v92 src0_sel:WORD_1
	v_cvt_pk_f32_fp8_e32 v[200:201], v93
	v_cvt_pk_f32_fp8_sdwa v[202:203], v93 src0_sel:WORD_1
	v_cvt_pk_f32_fp8_e32 v[216:217], v94
	v_cvt_pk_f32_fp8_sdwa v[218:219], v94 src0_sel:WORD_1
	v_cvt_pk_f32_fp8_e32 v[220:221], v95
	v_cvt_pk_f32_fp8_sdwa v[222:223], v95 src0_sel:WORD_1
	v_pk_fma_f32 v[6:7], v[142:143], v[196:197], v[6:7] op_sel:[1,0,0]
	v_pk_fma_f32 v[8:9], v[142:143], v[198:199], v[8:9] op_sel:[1,0,0]
	v_pk_fma_f32 v[10:11], v[142:143], v[200:201], v[10:11] op_sel:[1,0,0]
	v_pk_fma_f32 v[12:13], v[142:143], v[202:203], v[12:13] op_sel:[1,0,0]
	v_pk_fma_f32 v[14:15], v[142:143], v[216:217], v[14:15] op_sel:[1,0,0]
	v_pk_fma_f32 v[16:17], v[142:143], v[218:219], v[16:17] op_sel:[1,0,0]
	v_pk_fma_f32 v[2:3], v[142:143], v[220:221], v[2:3] op_sel:[1,0,0]
	v_pk_fma_f32 v[4:5], v[142:143], v[222:223], v[4:5] op_sel:[1,0,0]
	v_readfirstlane_b32 s30, v30
	s_ashr_i32 s31, s30, 31
	s_lshl_b64 s[30:31], s[30:31], 10
	v_lshl_add_u64 v[162:163], v[122:123], 0, s[30:31]
	global_load_dwordx4 v[92:95], v[162:163], off
	s_waitcnt vmcnt(15)
	v_cvt_pk_f32_fp8_e32 v[196:197], v96
	v_cvt_pk_f32_fp8_sdwa v[198:199], v96 src0_sel:WORD_1
	v_cvt_pk_f32_fp8_e32 v[200:201], v97
	v_cvt_pk_f32_fp8_sdwa v[202:203], v97 src0_sel:WORD_1
	v_cvt_pk_f32_fp8_e32 v[216:217], v98
	v_cvt_pk_f32_fp8_sdwa v[218:219], v98 src0_sel:WORD_1
	v_cvt_pk_f32_fp8_e32 v[220:221], v99
	v_cvt_pk_f32_fp8_sdwa v[222:223], v99 src0_sel:WORD_1
	v_pk_fma_f32 v[6:7], v[144:145], v[196:197], v[6:7] op_sel:[1,0,0]
	v_pk_fma_f32 v[8:9], v[144:145], v[198:199], v[8:9] op_sel:[1,0,0]
	v_pk_fma_f32 v[10:11], v[144:145], v[200:201], v[10:11] op_sel:[1,0,0]
	v_pk_fma_f32 v[12:13], v[144:145], v[202:203], v[12:13] op_sel:[1,0,0]
	v_pk_fma_f32 v[14:15], v[144:145], v[216:217], v[14:15] op_sel:[1,0,0]
	v_pk_fma_f32 v[16:17], v[144:145], v[218:219], v[16:17] op_sel:[1,0,0]
	v_pk_fma_f32 v[2:3], v[144:145], v[220:221], v[2:3] op_sel:[1,0,0]
	v_pk_fma_f32 v[4:5], v[144:145], v[222:223], v[4:5] op_sel:[1,0,0]
	v_readfirstlane_b32 s30, v32
	s_ashr_i32 s31, s30, 31
	s_lshl_b64 s[30:31], s[30:31], 10
	v_lshl_add_u64 v[162:163], v[122:123], 0, s[30:31]
	global_load_dwordx4 v[96:99], v[162:163], off
	s_waitcnt vmcnt(15)
	v_cvt_pk_f32_fp8_e32 v[196:197], v100
	v_cvt_pk_f32_fp8_sdwa v[198:199], v100 src0_sel:WORD_1
	v_cvt_pk_f32_fp8_e32 v[200:201], v101
	v_cvt_pk_f32_fp8_sdwa v[202:203], v101 src0_sel:WORD_1
	v_cvt_pk_f32_fp8_e32 v[216:217], v102
	v_cvt_pk_f32_fp8_sdwa v[218:219], v102 src0_sel:WORD_1
	v_cvt_pk_f32_fp8_e32 v[220:221], v103
	v_cvt_pk_f32_fp8_sdwa v[222:223], v103 src0_sel:WORD_1
	v_pk_fma_f32 v[6:7], v[146:147], v[196:197], v[6:7] op_sel:[1,0,0]
	v_pk_fma_f32 v[8:9], v[146:147], v[198:199], v[8:9] op_sel:[1,0,0]
	v_pk_fma_f32 v[10:11], v[146:147], v[200:201], v[10:11] op_sel:[1,0,0]
	v_pk_fma_f32 v[12:13], v[146:147], v[202:203], v[12:13] op_sel:[1,0,0]
	v_pk_fma_f32 v[14:15], v[146:147], v[216:217], v[14:15] op_sel:[1,0,0]
	v_pk_fma_f32 v[16:17], v[146:147], v[218:219], v[16:17] op_sel:[1,0,0]
	v_pk_fma_f32 v[2:3], v[146:147], v[220:221], v[2:3] op_sel:[1,0,0]
	v_pk_fma_f32 v[4:5], v[146:147], v[222:223], v[4:5] op_sel:[1,0,0]
	v_readfirstlane_b32 s30, v34
	s_ashr_i32 s31, s30, 31
	s_lshl_b64 s[30:31], s[30:31], 10
	v_lshl_add_u64 v[162:163], v[122:123], 0, s[30:31]
	global_load_dwordx4 v[100:103], v[162:163], off
	s_waitcnt vmcnt(15)
	v_cvt_pk_f32_fp8_e32 v[196:197], v104
	v_cvt_pk_f32_fp8_sdwa v[198:199], v104 src0_sel:WORD_1
	v_cvt_pk_f32_fp8_e32 v[200:201], v105
	v_cvt_pk_f32_fp8_sdwa v[202:203], v105 src0_sel:WORD_1
	v_cvt_pk_f32_fp8_e32 v[216:217], v106
	v_cvt_pk_f32_fp8_sdwa v[218:219], v106 src0_sel:WORD_1
	v_cvt_pk_f32_fp8_e32 v[220:221], v107
	v_cvt_pk_f32_fp8_sdwa v[222:223], v107 src0_sel:WORD_1
	v_pk_fma_f32 v[6:7], v[148:149], v[196:197], v[6:7] op_sel:[1,0,0]
	v_pk_fma_f32 v[8:9], v[148:149], v[198:199], v[8:9] op_sel:[1,0,0]
	v_pk_fma_f32 v[10:11], v[148:149], v[200:201], v[10:11] op_sel:[1,0,0]
	v_pk_fma_f32 v[12:13], v[148:149], v[202:203], v[12:13] op_sel:[1,0,0]
	v_pk_fma_f32 v[14:15], v[148:149], v[216:217], v[14:15] op_sel:[1,0,0]
	v_pk_fma_f32 v[16:17], v[148:149], v[218:219], v[16:17] op_sel:[1,0,0]
	v_pk_fma_f32 v[2:3], v[148:149], v[220:221], v[2:3] op_sel:[1,0,0]
	v_pk_fma_f32 v[4:5], v[148:149], v[222:223], v[4:5] op_sel:[1,0,0]
	v_readfirstlane_b32 s30, v36
	s_ashr_i32 s31, s30, 31
	s_lshl_b64 s[30:31], s[30:31], 10
	v_lshl_add_u64 v[162:163], v[122:123], 0, s[30:31]
	global_load_dwordx4 v[104:107], v[162:163], off
	s_waitcnt vmcnt(15)
	v_cvt_pk_f32_fp8_e32 v[196:197], v108
	v_cvt_pk_f32_fp8_sdwa v[198:199], v108 src0_sel:WORD_1
	v_cvt_pk_f32_fp8_e32 v[200:201], v109
	v_cvt_pk_f32_fp8_sdwa v[202:203], v109 src0_sel:WORD_1
	v_cvt_pk_f32_fp8_e32 v[216:217], v110
	v_cvt_pk_f32_fp8_sdwa v[218:219], v110 src0_sel:WORD_1
	v_cvt_pk_f32_fp8_e32 v[220:221], v111
	v_cvt_pk_f32_fp8_sdwa v[222:223], v111 src0_sel:WORD_1
	v_pk_fma_f32 v[6:7], v[150:151], v[196:197], v[6:7] op_sel:[1,0,0]
	v_pk_fma_f32 v[8:9], v[150:151], v[198:199], v[8:9] op_sel:[1,0,0]
	v_pk_fma_f32 v[10:11], v[150:151], v[200:201], v[10:11] op_sel:[1,0,0]
	v_pk_fma_f32 v[12:13], v[150:151], v[202:203], v[12:13] op_sel:[1,0,0]
	v_pk_fma_f32 v[14:15], v[150:151], v[216:217], v[14:15] op_sel:[1,0,0]
	v_pk_fma_f32 v[16:17], v[150:151], v[218:219], v[16:17] op_sel:[1,0,0]
	v_pk_fma_f32 v[2:3], v[150:151], v[220:221], v[2:3] op_sel:[1,0,0]
	v_pk_fma_f32 v[4:5], v[150:151], v[222:223], v[4:5] op_sel:[1,0,0]
	v_readfirstlane_b32 s30, v38
	s_ashr_i32 s31, s30, 31
	s_lshl_b64 s[30:31], s[30:31], 10
	v_lshl_add_u64 v[162:163], v[122:123], 0, s[30:31]
	global_load_dwordx4 v[108:111], v[162:163], off
	s_waitcnt vmcnt(15)
;     ...
;     for (int j0 = 0; j0 < NTL * 16; j0 += 16) {
;         u32x4_t w[16]; float cj[16];
; #pragma unroll
;         for (int jj = 0; jj < 16; ++jj) { const u32x2_t pr = pl[j0 + jj]; const int ej = __builtin_amdgcn_readfirstlane((int)pr.x); cj[jj] = __uint_as_float(pr.y);
;             w[jj] = *(const u32x4_t*)(v8 + (size_t)ej * D + 16 * lane); }
; #pragma unroll
;         for (int jj = 0; jj < 16; ++jj) { const float c = cj[jj];
; #pragma unroll
;             for (int q = 0; q < 4; ++q) { const f32x2_t lo = __builtin_amdgcn_cvt_pk_f32_fp8((int)w[jj][q], false), hi = __builtin_amdgcn_cvt_pk_f32_fp8((int)w[jj][q], true);
;                 o[4 * q] += c * lo[0]; o[4 * q + 1] += c * lo[1]; o[4 * q + 2] += c * hi[0]; o[4 * q + 3] += c * hi[1]; } }
	v_cvt_pk_f32_fp8_e32 v[196:197], v112
	v_cvt_pk_f32_fp8_sdwa v[198:199], v112 src0_sel:WORD_1
	v_cvt_pk_f32_fp8_e32 v[200:201], v113
	v_cvt_pk_f32_fp8_sdwa v[202:203], v113 src0_sel:WORD_1
	v_cvt_pk_f32_fp8_e32 v[216:217], v114
	v_cvt_pk_f32_fp8_sdwa v[218:219], v114 src0_sel:WORD_1
	v_cvt_pk_f32_fp8_e32 v[220:221], v115
	v_cvt_pk_f32_fp8_sdwa v[222:223], v115 src0_sel:WORD_1
	v_pk_fma_f32 v[6:7], v[152:153], v[196:197], v[6:7] op_sel:[1,0,0]
	v_pk_fma_f32 v[8:9], v[152:153], v[198:199], v[8:9] op_sel:[1,0,0]
	v_pk_fma_f32 v[10:11], v[152:153], v[200:201], v[10:11] op_sel:[1,0,0]
	v_pk_fma_f32 v[12:13], v[152:153], v[202:203], v[12:13] op_sel:[1,0,0]
	v_pk_fma_f32 v[14:15], v[152:153], v[216:217], v[14:15] op_sel:[1,0,0]
	v_pk_fma_f32 v[16:17], v[152:153], v[218:219], v[16:17] op_sel:[1,0,0]
	v_pk_fma_f32 v[2:3], v[152:153], v[220:221], v[2:3] op_sel:[1,0,0]
	v_pk_fma_f32 v[4:5], v[152:153], v[222:223], v[4:5] op_sel:[1,0,0]
	v_readfirstlane_b32 s30, v40
	s_ashr_i32 s31, s30, 31
	s_lshl_b64 s[30:31], s[30:31], 10
	v_lshl_add_u64 v[162:163], v[122:123], 0, s[30:31]
	global_load_dwordx4 v[112:115], v[162:163], off
	s_waitcnt vmcnt(15)
	v_cvt_pk_f32_fp8_e32 v[196:197], v180
	v_cvt_pk_f32_fp8_sdwa v[198:199], v180 src0_sel:WORD_1
	v_cvt_pk_f32_fp8_e32 v[200:201], v181
	v_cvt_pk_f32_fp8_sdwa v[202:203], v181 src0_sel:WORD_1
	v_cvt_pk_f32_fp8_e32 v[216:217], v182
	v_cvt_pk_f32_fp8_sdwa v[218:219], v182 src0_sel:WORD_1
	v_cvt_pk_f32_fp8_e32 v[220:221], v183
	v_cvt_pk_f32_fp8_sdwa v[222:223], v183 src0_sel:WORD_1
	v_pk_fma_f32 v[6:7], v[154:155], v[196:197], v[6:7] op_sel:[1,0,0]
	v_pk_fma_f32 v[8:9], v[154:155], v[198:199], v[8:9] op_sel:[1,0,0]
	v_pk_fma_f32 v[10:11], v[154:155], v[200:201], v[10:11] op_sel:[1,0,0]
	v_pk_fma_f32 v[12:13], v[154:155], v[202:203], v[12:13] op_sel:[1,0,0]
	v_pk_fma_f32 v[14:15], v[154:155], v[216:217], v[14:15] op_sel:[1,0,0]
	v_pk_fma_f32 v[16:17], v[154:155], v[218:219], v[16:17] op_sel:[1,0,0]
	v_pk_fma_f32 v[2:3], v[154:155], v[220:221], v[2:3] op_sel:[1,0,0]
	v_pk_fma_f32 v[4:5], v[154:155], v[222:223], v[4:5] op_sel:[1,0,0]
	v_readfirstlane_b32 s30, v42
	s_ashr_i32 s31, s30, 31
	s_lshl_b64 s[30:31], s[30:31], 10
	v_lshl_add_u64 v[162:163], v[122:123], 0, s[30:31]
	global_load_dwordx4 v[180:183], v[162:163], off
	s_waitcnt vmcnt(15)
	v_cvt_pk_f32_fp8_e32 v[196:197], v184
	v_cvt_pk_f32_fp8_sdwa v[198:199], v184 src0_sel:WORD_1
	v_cvt_pk_f32_fp8_e32 v[200:201], v185
	v_cvt_pk_f32_fp8_sdwa v[202:203], v185 src0_sel:WORD_1
	v_cvt_pk_f32_fp8_e32 v[216:217], v186
	v_cvt_pk_f32_fp8_sdwa v[218:219], v186 src0_sel:WORD_1
	v_cvt_pk_f32_fp8_e32 v[220:221], v187
	v_cvt_pk_f32_fp8_sdwa v[222:223], v187 src0_sel:WORD_1
	v_pk_fma_f32 v[6:7], v[156:157], v[196:197], v[6:7] op_sel:[1,0,0]
	v_pk_fma_f32 v[8:9], v[156:157], v[198:199], v[8:9] op_sel:[1,0,0]
	v_pk_fma_f32 v[10:11], v[156:157], v[200:201], v[10:11] op_sel:[1,0,0]
	v_pk_fma_f32 v[12:13], v[156:157], v[202:203], v[12:13] op_sel:[1,0,0]
	v_pk_fma_f32 v[14:15], v[156:157], v[216:217], v[14:15] op_sel:[1,0,0]
	v_pk_fma_f32 v[16:17], v[156:157], v[218:219], v[16:17] op_sel:[1,0,0]
	v_pk_fma_f32 v[2:3], v[156:157], v[220:221], v[2:3] op_sel:[1,0,0]
	v_pk_fma_f32 v[4:5], v[156:157], v[222:223], v[4:5] op_sel:[1,0,0]
	v_readfirstlane_b32 s30, v44
	s_ashr_i32 s31, s30, 31
	s_lshl_b64 s[30:31], s[30:31], 10
	v_lshl_add_u64 v[162:163], v[122:123], 0, s[30:31]
	global_load_dwordx4 v[184:187], v[162:163], off
	s_waitcnt vmcnt(15)
	v_cvt_pk_f32_fp8_e32 v[196:197], v188
	v_cvt_pk_f32_fp8_sdwa v[198:199], v188 src0_sel:WORD_1
	v_cvt_pk_f32_fp8_e32 v[200:201], v189
	v_cvt_pk_f32_fp8_sdwa v[202:203], v189 src0_sel:WORD_1
	v_cvt_pk_f32_fp8_e32 v[216:217], v190
	v_cvt_pk_f32_fp8_sdwa v[218:219], v190 src0_sel:WORD_1
	v_cvt_pk_f32_fp8_e32 v[220:221], v191
	v_cvt_pk_f32_fp8_sdwa v[222:223], v191 src0_sel:WORD_1
	v_pk_fma_f32 v[6:7], v[158:159], v[196:197], v[6:7] op_sel:[1,0,0]
	v_pk_fma_f32 v[8:9], v[158:159], v[198:199], v[8:9] op_sel:[1,0,0]
	v_pk_fma_f32 v[10:11], v[158:159], v[200:201], v[10:11] op_sel:[1,0,0]
	v_pk_fma_f32 v[12:13], v[158:159], v[202:203], v[12:13] op_sel:[1,0,0]
	v_pk_fma_f32 v[14:15], v[158:159], v[216:217], v[14:15] op_sel:[1,0,0]
	v_pk_fma_f32 v[16:17], v[158:159], v[218:219], v[16:17] op_sel:[1,0,0]
	v_pk_fma_f32 v[2:3], v[158:159], v[220:221], v[2:3] op_sel:[1,0,0]
	v_pk_fma_f32 v[4:5], v[158:159], v[222:223], v[4:5] op_sel:[1,0,0]
	v_readfirstlane_b32 s30, v46
	s_ashr_i32 s31, s30, 31
	s_lshl_b64 s[30:31], s[30:31], 10
	v_lshl_add_u64 v[162:163], v[122:123], 0, s[30:31]
	global_load_dwordx4 v[188:191], v[162:163], off
	s_waitcnt vmcnt(15)
	v_cvt_pk_f32_fp8_e32 v[196:197], v192
	v_cvt_pk_f32_fp8_sdwa v[198:199], v192 src0_sel:WORD_1
	v_cvt_pk_f32_fp8_e32 v[200:201], v193
	v_cvt_pk_f32_fp8_sdwa v[202:203], v193 src0_sel:WORD_1
	v_cvt_pk_f32_fp8_e32 v[216:217], v194
	v_cvt_pk_f32_fp8_sdwa v[218:219], v194 src0_sel:WORD_1
	v_cvt_pk_f32_fp8_e32 v[220:221], v195
	v_cvt_pk_f32_fp8_sdwa v[222:223], v195 src0_sel:WORD_1
	v_pk_fma_f32 v[6:7], v[160:161], v[196:197], v[6:7] op_sel:[1,0,0]
	v_pk_fma_f32 v[8:9], v[160:161], v[198:199], v[8:9] op_sel:[1,0,0]
	v_pk_fma_f32 v[10:11], v[160:161], v[200:201], v[10:11] op_sel:[1,0,0]
	v_pk_fma_f32 v[12:13], v[160:161], v[202:203], v[12:13] op_sel:[1,0,0]
	v_pk_fma_f32 v[14:15], v[160:161], v[216:217], v[14:15] op_sel:[1,0,0]
	v_pk_fma_f32 v[16:17], v[160:161], v[218:219], v[16:17] op_sel:[1,0,0]
	v_pk_fma_f32 v[2:3], v[160:161], v[220:221], v[2:3] op_sel:[1,0,0]
	v_pk_fma_f32 v[4:5], v[160:161], v[222:223], v[4:5] op_sel:[1,0,0]
	v_readfirstlane_b32 s30, v48
	s_ashr_i32 s31, s30, 31
	s_lshl_b64 s[30:31], s[30:31], 10
	v_lshl_add_u64 v[162:163], v[122:123], 0, s[30:31]
	global_load_dwordx4 v[192:195], v[162:163], off
	ds_read_b128 v[130:133], v164 offset:384
	ds_read_b128 v[134:137], v164 offset:400
	ds_read_b128 v[138:141], v164 offset:416
	ds_read_b128 v[142:145], v164 offset:432
	ds_read_b128 v[146:149], v164 offset:448
	ds_read_b128 v[150:153], v164 offset:464
	ds_read_b128 v[154:157], v164 offset:480
	ds_read_b128 v[158:161], v164 offset:496
	s_waitcnt lgkmcnt(0)
;     ...
;     for (int j0 = 0; j0 < NTL * 16; j0 += 16) {
;         u32x4_t w[16]; float cj[16];
; #pragma unroll
;         for (int jj = 0; jj < 16; ++jj) { const u32x2_t pr = pl[j0 + jj]; const int ej = __builtin_amdgcn_readfirstlane((int)pr.x); cj[jj] = __uint_as_float(pr.y);
;             w[jj] = *(const u32x4_t*)(v8 + (size_t)ej * D + 16 * lane); }
; #pragma unroll
;         for (int jj = 0; jj < 16; ++jj) { const float c = cj[jj];
; #pragma unroll
;             for (int q = 0; q < 4; ++q) { const f32x2_t lo = __builtin_amdgcn_cvt_pk_f32_fp8((int)w[jj][q], false), hi = __builtin_amdgcn_cvt_pk_f32_fp8((int)w[jj][q], true);
;                 o[4 * q] += c * lo[0]; o[4 * q + 1] += c * lo[1]; o[4 * q + 2] += c * hi[0]; o[4 * q + 3] += c * hi[1]; } }
	s_waitcnt vmcnt(15)
	v_cvt_pk_f32_fp8_e32 v[196:197], v68
	v_cvt_pk_f32_fp8_sdwa v[198:199], v68 src0_sel:WORD_1
	v_cvt_pk_f32_fp8_e32 v[200:201], v69
	v_cvt_pk_f32_fp8_sdwa v[202:203], v69 src0_sel:WORD_1
	v_cvt_pk_f32_fp8_e32 v[216:217], v70
	v_cvt_pk_f32_fp8_sdwa v[218:219], v70 src0_sel:WORD_1
	v_cvt_pk_f32_fp8_e32 v[220:221], v71
	v_cvt_pk_f32_fp8_sdwa v[222:223], v71 src0_sel:WORD_1
	v_pk_fma_f32 v[6:7], v[18:19], v[196:197], v[6:7] op_sel:[1,0,0]
	v_pk_fma_f32 v[8:9], v[18:19], v[198:199], v[8:9] op_sel:[1,0,0]
	v_pk_fma_f32 v[10:11], v[18:19], v[200:201], v[10:11] op_sel:[1,0,0]
	v_pk_fma_f32 v[12:13], v[18:19], v[202:203], v[12:13] op_sel:[1,0,0]
	v_pk_fma_f32 v[14:15], v[18:19], v[216:217], v[14:15] op_sel:[1,0,0]
	v_pk_fma_f32 v[16:17], v[18:19], v[218:219], v[16:17] op_sel:[1,0,0]
	v_pk_fma_f32 v[2:3], v[18:19], v[220:221], v[2:3] op_sel:[1,0,0]
	v_pk_fma_f32 v[4:5], v[18:19], v[222:223], v[4:5] op_sel:[1,0,0]
	v_readfirstlane_b32 s30, v130
	s_ashr_i32 s31, s30, 31
	s_lshl_b64 s[30:31], s[30:31], 10
	v_lshl_add_u64 v[162:163], v[122:123], 0, s[30:31]
	global_load_dwordx4 v[68:71], v[162:163], off
	s_waitcnt vmcnt(15)
	v_cvt_pk_f32_fp8_e32 v[196:197], v72
	v_cvt_pk_f32_fp8_sdwa v[198:199], v72 src0_sel:WORD_1
	v_cvt_pk_f32_fp8_e32 v[200:201], v73
	v_cvt_pk_f32_fp8_sdwa v[202:203], v73 src0_sel:WORD_1
	v_cvt_pk_f32_fp8_e32 v[216:217], v74
	v_cvt_pk_f32_fp8_sdwa v[218:219], v74 src0_sel:WORD_1
	v_cvt_pk_f32_fp8_e32 v[220:221], v75
	v_cvt_pk_f32_fp8_sdwa v[222:223], v75 src0_sel:WORD_1
	v_pk_fma_f32 v[6:7], v[20:21], v[196:197], v[6:7] op_sel:[1,0,0]
	v_pk_fma_f32 v[8:9], v[20:21], v[198:199], v[8:9] op_sel:[1,0,0]
	v_pk_fma_f32 v[10:11], v[20:21], v[200:201], v[10:11] op_sel:[1,0,0]
	v_pk_fma_f32 v[12:13], v[20:21], v[202:203], v[12:13] op_sel:[1,0,0]
	v_pk_fma_f32 v[14:15], v[20:21], v[216:217], v[14:15] op_sel:[1,0,0]
	v_pk_fma_f32 v[16:17], v[20:21], v[218:219], v[16:17] op_sel:[1,0,0]
	v_pk_fma_f32 v[2:3], v[20:21], v[220:221], v[2:3] op_sel:[1,0,0]
	v_pk_fma_f32 v[4:5], v[20:21], v[222:223], v[4:5] op_sel:[1,0,0]
	v_readfirstlane_b32 s30, v132
	s_ashr_i32 s31, s30, 31
	s_lshl_b64 s[30:31], s[30:31], 10
	v_lshl_add_u64 v[162:163], v[122:123], 0, s[30:31]
	global_load_dwordx4 v[72:75], v[162:163], off
	s_waitcnt vmcnt(15)
	v_cvt_pk_f32_fp8_e32 v[196:197], v76
	v_cvt_pk_f32_fp8_sdwa v[198:199], v76 src0_sel:WORD_1
	v_cvt_pk_f32_fp8_e32 v[200:201], v77
	v_cvt_pk_f32_fp8_sdwa v[202:203], v77 src0_sel:WORD_1
	v_cvt_pk_f32_fp8_e32 v[216:217], v78
	v_cvt_pk_f32_fp8_sdwa v[218:219], v78 src0_sel:WORD_1
	v_cvt_pk_f32_fp8_e32 v[220:221], v79
	v_cvt_pk_f32_fp8_sdwa v[222:223], v79 src0_sel:WORD_1
	v_pk_fma_f32 v[6:7], v[22:23], v[196:197], v[6:7] op_sel:[1,0,0]
	v_pk_fma_f32 v[8:9], v[22:23], v[198:199], v[8:9] op_sel:[1,0,0]
	v_pk_fma_f32 v[10:11], v[22:23], v[200:201], v[10:11] op_sel:[1,0,0]
	v_pk_fma_f32 v[12:13], v[22:23], v[202:203], v[12:13] op_sel:[1,0,0]
	v_pk_fma_f32 v[14:15], v[22:23], v[216:217], v[14:15] op_sel:[1,0,0]
	v_pk_fma_f32 v[16:17], v[22:23], v[218:219], v[16:17] op_sel:[1,0,0]
	v_pk_fma_f32 v[2:3], v[22:23], v[220:221], v[2:3] op_sel:[1,0,0]
	v_pk_fma_f32 v[4:5], v[22:23], v[222:223], v[4:5] op_sel:[1,0,0]
	v_readfirstlane_b32 s30, v134
	s_ashr_i32 s31, s30, 31
	s_lshl_b64 s[30:31], s[30:31], 10
	v_lshl_add_u64 v[162:163], v[122:123], 0, s[30:31]
	global_load_dwordx4 v[76:79], v[162:163], off
	s_waitcnt vmcnt(15)
	v_cvt_pk_f32_fp8_e32 v[196:197], v80
	v_cvt_pk_f32_fp8_sdwa v[198:199], v80 src0_sel:WORD_1
	v_cvt_pk_f32_fp8_e32 v[200:201], v81
	v_cvt_pk_f32_fp8_sdwa v[202:203], v81 src0_sel:WORD_1
	v_cvt_pk_f32_fp8_e32 v[216:217], v82
	v_cvt_pk_f32_fp8_sdwa v[218:219], v82 src0_sel:WORD_1
	v_cvt_pk_f32_fp8_e32 v[220:221], v83
	v_cvt_pk_f32_fp8_sdwa v[222:223], v83 src0_sel:WORD_1
	v_pk_fma_f32 v[6:7], v[24:25], v[196:197], v[6:7] op_sel:[1,0,0]
	v_pk_fma_f32 v[8:9], v[24:25], v[198:199], v[8:9] op_sel:[1,0,0]
	v_pk_fma_f32 v[10:11], v[24:25], v[200:201], v[10:11] op_sel:[1,0,0]
	v_pk_fma_f32 v[12:13], v[24:25], v[202:203], v[12:13] op_sel:[1,0,0]
	v_pk_fma_f32 v[14:15], v[24:25], v[216:217], v[14:15] op_sel:[1,0,0]
	v_pk_fma_f32 v[16:17], v[24:25], v[218:219], v[16:17] op_sel:[1,0,0]
	v_pk_fma_f32 v[2:3], v[24:25], v[220:221], v[2:3] op_sel:[1,0,0]
	v_pk_fma_f32 v[4:5], v[24:25], v[222:223], v[4:5] op_sel:[1,0,0]
	v_readfirstlane_b32 s30, v136
	s_ashr_i32 s31, s30, 31
	s_lshl_b64 s[30:31], s[30:31], 10
	v_lshl_add_u64 v[162:163], v[122:123], 0, s[30:31]
	global_load_dwordx4 v[80:83], v[162:163], off
	s_waitcnt vmcnt(15)
	v_cvt_pk_f32_fp8_e32 v[196:197], v84
	v_cvt_pk_f32_fp8_sdwa v[198:199], v84 src0_sel:WORD_1
	v_cvt_pk_f32_fp8_e32 v[200:201], v85
	v_cvt_pk_f32_fp8_sdwa v[202:203], v85 src0_sel:WORD_1
	v_cvt_pk_f32_fp8_e32 v[216:217], v86
	v_cvt_pk_f32_fp8_sdwa v[218:219], v86 src0_sel:WORD_1
	v_cvt_pk_f32_fp8_e32 v[220:221], v87
	v_cvt_pk_f32_fp8_sdwa v[222:223], v87 src0_sel:WORD_1
	v_pk_fma_f32 v[6:7], v[26:27], v[196:197], v[6:7] op_sel:[1,0,0]
	v_pk_fma_f32 v[8:9], v[26:27], v[198:199], v[8:9] op_sel:[1,0,0]
	v_pk_fma_f32 v[10:11], v[26:27], v[200:201], v[10:11] op_sel:[1,0,0]
	v_pk_fma_f32 v[12:13], v[26:27], v[202:203], v[12:13] op_sel:[1,0,0]
	v_pk_fma_f32 v[14:15], v[26:27], v[216:217], v[14:15] op_sel:[1,0,0]
	v_pk_fma_f32 v[16:17], v[26:27], v[218:219], v[16:17] op_sel:[1,0,0]
	v_pk_fma_f32 v[2:3], v[26:27], v[220:221], v[2:3] op_sel:[1,0,0]
	v_pk_fma_f32 v[4:5], v[26:27], v[222:223], v[4:5] op_sel:[1,0,0]
	v_readfirstlane_b32 s30, v138
	s_ashr_i32 s31, s30, 31
	s_lshl_b64 s[30:31], s[30:31], 10
	v_lshl_add_u64 v[162:163], v[122:123], 0, s[30:31]
	global_load_dwordx4 v[84:87], v[162:163], off
	s_waitcnt vmcnt(15)
;     ...
;     for (int j0 = 0; j0 < NTL * 16; j0 += 16) {
;         u32x4_t w[16]; float cj[16];
; #pragma unroll
;         for (int jj = 0; jj < 16; ++jj) { const u32x2_t pr = pl[j0 + jj]; const int ej = __builtin_amdgcn_readfirstlane((int)pr.x); cj[jj] = __uint_as_float(pr.y);
;             w[jj] = *(const u32x4_t*)(v8 + (size_t)ej * D + 16 * lane); }
; #pragma unroll
;         for (int jj = 0; jj < 16; ++jj) { const float c = cj[jj];
; #pragma unroll
;             for (int q = 0; q < 4; ++q) { const f32x2_t lo = __builtin_amdgcn_cvt_pk_f32_fp8((int)w[jj][q], false), hi = __builtin_amdgcn_cvt_pk_f32_fp8((int)w[jj][q], true);
;                 o[4 * q] += c * lo[0]; o[4 * q + 1] += c * lo[1]; o[4 * q + 2] += c * hi[0]; o[4 * q + 3] += c * hi[1]; } }
	v_cvt_pk_f32_fp8_e32 v[196:197], v88
	v_cvt_pk_f32_fp8_sdwa v[198:199], v88 src0_sel:WORD_1
	v_cvt_pk_f32_fp8_e32 v[200:201], v89
	v_cvt_pk_f32_fp8_sdwa v[202:203], v89 src0_sel:WORD_1
	v_cvt_pk_f32_fp8_e32 v[216:217], v90
	v_cvt_pk_f32_fp8_sdwa v[218:219], v90 src0_sel:WORD_1
	v_cvt_pk_f32_fp8_e32 v[220:221], v91
	v_cvt_pk_f32_fp8_sdwa v[222:223], v91 src0_sel:WORD_1
	v_pk_fma_f32 v[6:7], v[28:29], v[196:197], v[6:7] op_sel:[1,0,0]
	v_pk_fma_f32 v[8:9], v[28:29], v[198:199], v[8:9] op_sel:[1,0,0]
	v_pk_fma_f32 v[10:11], v[28:29], v[200:201], v[10:11] op_sel:[1,0,0]
	v_pk_fma_f32 v[12:13], v[28:29], v[202:203], v[12:13] op_sel:[1,0,0]
	v_pk_fma_f32 v[14:15], v[28:29], v[216:217], v[14:15] op_sel:[1,0,0]
	v_pk_fma_f32 v[16:17], v[28:29], v[218:219], v[16:17] op_sel:[1,0,0]
	v_pk_fma_f32 v[2:3], v[28:29], v[220:221], v[2:3] op_sel:[1,0,0]
	v_pk_fma_f32 v[4:5], v[28:29], v[222:223], v[4:5] op_sel:[1,0,0]
	v_readfirstlane_b32 s30, v140
	s_ashr_i32 s31, s30, 31
	s_lshl_b64 s[30:31], s[30:31], 10
	v_lshl_add_u64 v[162:163], v[122:123], 0, s[30:31]
	global_load_dwordx4 v[88:91], v[162:163], off
	s_waitcnt vmcnt(15)
	v_cvt_pk_f32_fp8_e32 v[196:197], v92
	v_cvt_pk_f32_fp8_sdwa v[198:199], v92 src0_sel:WORD_1
	v_cvt_pk_f32_fp8_e32 v[200:201], v93
	v_cvt_pk_f32_fp8_sdwa v[202:203], v93 src0_sel:WORD_1
	v_cvt_pk_f32_fp8_e32 v[216:217], v94
	v_cvt_pk_f32_fp8_sdwa v[218:219], v94 src0_sel:WORD_1
	v_cvt_pk_f32_fp8_e32 v[220:221], v95
	v_cvt_pk_f32_fp8_sdwa v[222:223], v95 src0_sel:WORD_1
	v_pk_fma_f32 v[6:7], v[30:31], v[196:197], v[6:7] op_sel:[1,0,0]
	v_pk_fma_f32 v[8:9], v[30:31], v[198:199], v[8:9] op_sel:[1,0,0]
	v_pk_fma_f32 v[10:11], v[30:31], v[200:201], v[10:11] op_sel:[1,0,0]
	v_pk_fma_f32 v[12:13], v[30:31], v[202:203], v[12:13] op_sel:[1,0,0]
	v_pk_fma_f32 v[14:15], v[30:31], v[216:217], v[14:15] op_sel:[1,0,0]
	v_pk_fma_f32 v[16:17], v[30:31], v[218:219], v[16:17] op_sel:[1,0,0]
	v_pk_fma_f32 v[2:3], v[30:31], v[220:221], v[2:3] op_sel:[1,0,0]
	v_pk_fma_f32 v[4:5], v[30:31], v[222:223], v[4:5] op_sel:[1,0,0]
	v_readfirstlane_b32 s30, v142
	s_ashr_i32 s31, s30, 31
	s_lshl_b64 s[30:31], s[30:31], 10
	v_lshl_add_u64 v[162:163], v[122:123], 0, s[30:31]
	global_load_dwordx4 v[92:95], v[162:163], off
	s_waitcnt vmcnt(15)
	v_cvt_pk_f32_fp8_e32 v[196:197], v96
	v_cvt_pk_f32_fp8_sdwa v[198:199], v96 src0_sel:WORD_1
	v_cvt_pk_f32_fp8_e32 v[200:201], v97
	v_cvt_pk_f32_fp8_sdwa v[202:203], v97 src0_sel:WORD_1
	v_cvt_pk_f32_fp8_e32 v[216:217], v98
	v_cvt_pk_f32_fp8_sdwa v[218:219], v98 src0_sel:WORD_1
	v_cvt_pk_f32_fp8_e32 v[220:221], v99
	v_cvt_pk_f32_fp8_sdwa v[222:223], v99 src0_sel:WORD_1
	v_pk_fma_f32 v[6:7], v[32:33], v[196:197], v[6:7] op_sel:[1,0,0]
	v_pk_fma_f32 v[8:9], v[32:33], v[198:199], v[8:9] op_sel:[1,0,0]
	v_pk_fma_f32 v[10:11], v[32:33], v[200:201], v[10:11] op_sel:[1,0,0]
	v_pk_fma_f32 v[12:13], v[32:33], v[202:203], v[12:13] op_sel:[1,0,0]
	v_pk_fma_f32 v[14:15], v[32:33], v[216:217], v[14:15] op_sel:[1,0,0]
	v_pk_fma_f32 v[16:17], v[32:33], v[218:219], v[16:17] op_sel:[1,0,0]
	v_pk_fma_f32 v[2:3], v[32:33], v[220:221], v[2:3] op_sel:[1,0,0]
	v_pk_fma_f32 v[4:5], v[32:33], v[222:223], v[4:5] op_sel:[1,0,0]
	v_readfirstlane_b32 s30, v144
	s_ashr_i32 s31, s30, 31
	s_lshl_b64 s[30:31], s[30:31], 10
	v_lshl_add_u64 v[162:163], v[122:123], 0, s[30:31]
	global_load_dwordx4 v[96:99], v[162:163], off
	s_waitcnt vmcnt(15)
	v_cvt_pk_f32_fp8_e32 v[196:197], v100
	v_cvt_pk_f32_fp8_sdwa v[198:199], v100 src0_sel:WORD_1
	v_cvt_pk_f32_fp8_e32 v[200:201], v101
	v_cvt_pk_f32_fp8_sdwa v[202:203], v101 src0_sel:WORD_1
	v_cvt_pk_f32_fp8_e32 v[216:217], v102
	v_cvt_pk_f32_fp8_sdwa v[218:219], v102 src0_sel:WORD_1
	v_cvt_pk_f32_fp8_e32 v[220:221], v103
	v_cvt_pk_f32_fp8_sdwa v[222:223], v103 src0_sel:WORD_1
	v_pk_fma_f32 v[6:7], v[34:35], v[196:197], v[6:7] op_sel:[1,0,0]
	v_pk_fma_f32 v[8:9], v[34:35], v[198:199], v[8:9] op_sel:[1,0,0]
	v_pk_fma_f32 v[10:11], v[34:35], v[200:201], v[10:11] op_sel:[1,0,0]
	v_pk_fma_f32 v[12:13], v[34:35], v[202:203], v[12:13] op_sel:[1,0,0]
	v_pk_fma_f32 v[14:15], v[34:35], v[216:217], v[14:15] op_sel:[1,0,0]
	v_pk_fma_f32 v[16:17], v[34:35], v[218:219], v[16:17] op_sel:[1,0,0]
	v_pk_fma_f32 v[2:3], v[34:35], v[220:221], v[2:3] op_sel:[1,0,0]
	v_pk_fma_f32 v[4:5], v[34:35], v[222:223], v[4:5] op_sel:[1,0,0]
	v_readfirstlane_b32 s30, v146
	s_ashr_i32 s31, s30, 31
	s_lshl_b64 s[30:31], s[30:31], 10
	v_lshl_add_u64 v[162:163], v[122:123], 0, s[30:31]
	global_load_dwordx4 v[100:103], v[162:163], off
	s_waitcnt vmcnt(15)
	v_cvt_pk_f32_fp8_e32 v[196:197], v104
	v_cvt_pk_f32_fp8_sdwa v[198:199], v104 src0_sel:WORD_1
	v_cvt_pk_f32_fp8_e32 v[200:201], v105
	v_cvt_pk_f32_fp8_sdwa v[202:203], v105 src0_sel:WORD_1
	v_cvt_pk_f32_fp8_e32 v[216:217], v106
	v_cvt_pk_f32_fp8_sdwa v[218:219], v106 src0_sel:WORD_1
	v_cvt_pk_f32_fp8_e32 v[220:221], v107
	v_cvt_pk_f32_fp8_sdwa v[222:223], v107 src0_sel:WORD_1
	v_pk_fma_f32 v[6:7], v[36:37], v[196:197], v[6:7] op_sel:[1,0,0]
	v_pk_fma_f32 v[8:9], v[36:37], v[198:199], v[8:9] op_sel:[1,0,0]
	v_pk_fma_f32 v[10:11], v[36:37], v[200:201], v[10:11] op_sel:[1,0,0]
	v_pk_fma_f32 v[12:13], v[36:37], v[202:203], v[12:13] op_sel:[1,0,0]
	v_pk_fma_f32 v[14:15], v[36:37], v[216:217], v[14:15] op_sel:[1,0,0]
	v_pk_fma_f32 v[16:17], v[36:37], v[218:219], v[16:17] op_sel:[1,0,0]
	v_pk_fma_f32 v[2:3], v[36:37], v[220:221], v[2:3] op_sel:[1,0,0]
	v_pk_fma_f32 v[4:5], v[36:37], v[222:223], v[4:5] op_sel:[1,0,0]
	v_readfirstlane_b32 s30, v148
	s_ashr_i32 s31, s30, 31
	s_lshl_b64 s[30:31], s[30:31], 10
	v_lshl_add_u64 v[162:163], v[122:123], 0, s[30:31]
	global_load_dwordx4 v[104:107], v[162:163], off
	s_waitcnt vmcnt(15)
;     ...
;     for (int j0 = 0; j0 < NTL * 16; j0 += 16) {
;         u32x4_t w[16]; float cj[16];
; #pragma unroll
;         for (int jj = 0; jj < 16; ++jj) { const u32x2_t pr = pl[j0 + jj]; const int ej = __builtin_amdgcn_readfirstlane((int)pr.x); cj[jj] = __uint_as_float(pr.y);
;             w[jj] = *(const u32x4_t*)(v8 + (size_t)ej * D + 16 * lane); }
; #pragma unroll
;         for (int jj = 0; jj < 16; ++jj) { const float c = cj[jj];
; #pragma unroll
;             for (int q = 0; q < 4; ++q) { const f32x2_t lo = __builtin_amdgcn_cvt_pk_f32_fp8((int)w[jj][q], false), hi = __builtin_amdgcn_cvt_pk_f32_fp8((int)w[jj][q], true);
;                 o[4 * q] += c * lo[0]; o[4 * q + 1] += c * lo[1]; o[4 * q + 2] += c * hi[0]; o[4 * q + 3] += c * hi[1]; } }
	v_cvt_pk_f32_fp8_e32 v[196:197], v108
	v_cvt_pk_f32_fp8_sdwa v[198:199], v108 src0_sel:WORD_1
	v_cvt_pk_f32_fp8_e32 v[200:201], v109
	v_cvt_pk_f32_fp8_sdwa v[202:203], v109 src0_sel:WORD_1
	v_cvt_pk_f32_fp8_e32 v[216:217], v110
	v_cvt_pk_f32_fp8_sdwa v[218:219], v110 src0_sel:WORD_1
	v_cvt_pk_f32_fp8_e32 v[220:221], v111
	v_cvt_pk_f32_fp8_sdwa v[222:223], v111 src0_sel:WORD_1
	v_pk_fma_f32 v[6:7], v[38:39], v[196:197], v[6:7] op_sel:[1,0,0]
	v_pk_fma_f32 v[8:9], v[38:39], v[198:199], v[8:9] op_sel:[1,0,0]
	v_pk_fma_f32 v[10:11], v[38:39], v[200:201], v[10:11] op_sel:[1,0,0]
	v_pk_fma_f32 v[12:13], v[38:39], v[202:203], v[12:13] op_sel:[1,0,0]
	v_pk_fma_f32 v[14:15], v[38:39], v[216:217], v[14:15] op_sel:[1,0,0]
	v_pk_fma_f32 v[16:17], v[38:39], v[218:219], v[16:17] op_sel:[1,0,0]
	v_pk_fma_f32 v[2:3], v[38:39], v[220:221], v[2:3] op_sel:[1,0,0]
	v_pk_fma_f32 v[4:5], v[38:39], v[222:223], v[4:5] op_sel:[1,0,0]
	v_readfirstlane_b32 s30, v150
	s_ashr_i32 s31, s30, 31
	s_lshl_b64 s[30:31], s[30:31], 10
	v_lshl_add_u64 v[162:163], v[122:123], 0, s[30:31]
	global_load_dwordx4 v[108:111], v[162:163], off
	s_waitcnt vmcnt(15)
	v_cvt_pk_f32_fp8_e32 v[196:197], v112
	v_cvt_pk_f32_fp8_sdwa v[198:199], v112 src0_sel:WORD_1
	v_cvt_pk_f32_fp8_e32 v[200:201], v113
	v_cvt_pk_f32_fp8_sdwa v[202:203], v113 src0_sel:WORD_1
	v_cvt_pk_f32_fp8_e32 v[216:217], v114
	v_cvt_pk_f32_fp8_sdwa v[218:219], v114 src0_sel:WORD_1
	v_cvt_pk_f32_fp8_e32 v[220:221], v115
	v_cvt_pk_f32_fp8_sdwa v[222:223], v115 src0_sel:WORD_1
	v_pk_fma_f32 v[6:7], v[40:41], v[196:197], v[6:7] op_sel:[1,0,0]
	v_pk_fma_f32 v[8:9], v[40:41], v[198:199], v[8:9] op_sel:[1,0,0]
	v_pk_fma_f32 v[10:11], v[40:41], v[200:201], v[10:11] op_sel:[1,0,0]
	v_pk_fma_f32 v[12:13], v[40:41], v[202:203], v[12:13] op_sel:[1,0,0]
	v_pk_fma_f32 v[14:15], v[40:41], v[216:217], v[14:15] op_sel:[1,0,0]
	v_pk_fma_f32 v[16:17], v[40:41], v[218:219], v[16:17] op_sel:[1,0,0]
	v_pk_fma_f32 v[2:3], v[40:41], v[220:221], v[2:3] op_sel:[1,0,0]
	v_pk_fma_f32 v[4:5], v[40:41], v[222:223], v[4:5] op_sel:[1,0,0]
	v_readfirstlane_b32 s30, v152
	s_ashr_i32 s31, s30, 31
	s_lshl_b64 s[30:31], s[30:31], 10
	v_lshl_add_u64 v[162:163], v[122:123], 0, s[30:31]
	global_load_dwordx4 v[112:115], v[162:163], off
	s_waitcnt vmcnt(15)
	v_cvt_pk_f32_fp8_e32 v[196:197], v180
	v_cvt_pk_f32_fp8_sdwa v[198:199], v180 src0_sel:WORD_1
	v_cvt_pk_f32_fp8_e32 v[200:201], v181
	v_cvt_pk_f32_fp8_sdwa v[202:203], v181 src0_sel:WORD_1
	v_cvt_pk_f32_fp8_e32 v[216:217], v182
	v_cvt_pk_f32_fp8_sdwa v[218:219], v182 src0_sel:WORD_1
	v_cvt_pk_f32_fp8_e32 v[220:221], v183
	v_cvt_pk_f32_fp8_sdwa v[222:223], v183 src0_sel:WORD_1
	v_pk_fma_f32 v[6:7], v[42:43], v[196:197], v[6:7] op_sel:[1,0,0]
	v_pk_fma_f32 v[8:9], v[42:43], v[198:199], v[8:9] op_sel:[1,0,0]
	v_pk_fma_f32 v[10:11], v[42:43], v[200:201], v[10:11] op_sel:[1,0,0]
	v_pk_fma_f32 v[12:13], v[42:43], v[202:203], v[12:13] op_sel:[1,0,0]
	v_pk_fma_f32 v[14:15], v[42:43], v[216:217], v[14:15] op_sel:[1,0,0]
	v_pk_fma_f32 v[16:17], v[42:43], v[218:219], v[16:17] op_sel:[1,0,0]
	v_pk_fma_f32 v[2:3], v[42:43], v[220:221], v[2:3] op_sel:[1,0,0]
	v_pk_fma_f32 v[4:5], v[42:43], v[222:223], v[4:5] op_sel:[1,0,0]
	v_readfirstlane_b32 s30, v154
	s_ashr_i32 s31, s30, 31
	s_lshl_b64 s[30:31], s[30:31], 10
	v_lshl_add_u64 v[162:163], v[122:123], 0, s[30:31]
	global_load_dwordx4 v[180:183], v[162:163], off
	s_waitcnt vmcnt(15)
	v_cvt_pk_f32_fp8_e32 v[196:197], v184
	v_cvt_pk_f32_fp8_sdwa v[198:199], v184 src0_sel:WORD_1
	v_cvt_pk_f32_fp8_e32 v[200:201], v185
	v_cvt_pk_f32_fp8_sdwa v[202:203], v185 src0_sel:WORD_1
	v_cvt_pk_f32_fp8_e32 v[216:217], v186
	v_cvt_pk_f32_fp8_sdwa v[218:219], v186 src0_sel:WORD_1
	v_cvt_pk_f32_fp8_e32 v[220:221], v187
	v_cvt_pk_f32_fp8_sdwa v[222:223], v187 src0_sel:WORD_1
	v_pk_fma_f32 v[6:7], v[44:45], v[196:197], v[6:7] op_sel:[1,0,0]
	v_pk_fma_f32 v[8:9], v[44:45], v[198:199], v[8:9] op_sel:[1,0,0]
	v_pk_fma_f32 v[10:11], v[44:45], v[200:201], v[10:11] op_sel:[1,0,0]
	v_pk_fma_f32 v[12:13], v[44:45], v[202:203], v[12:13] op_sel:[1,0,0]
	v_pk_fma_f32 v[14:15], v[44:45], v[216:217], v[14:15] op_sel:[1,0,0]
	v_pk_fma_f32 v[16:17], v[44:45], v[218:219], v[16:17] op_sel:[1,0,0]
	v_pk_fma_f32 v[2:3], v[44:45], v[220:221], v[2:3] op_sel:[1,0,0]
	v_pk_fma_f32 v[4:5], v[44:45], v[222:223], v[4:5] op_sel:[1,0,0]
	v_readfirstlane_b32 s30, v156
	s_ashr_i32 s31, s30, 31
	s_lshl_b64 s[30:31], s[30:31], 10
	v_lshl_add_u64 v[162:163], v[122:123], 0, s[30:31]
	global_load_dwordx4 v[184:187], v[162:163], off
	s_waitcnt vmcnt(15)
	v_cvt_pk_f32_fp8_e32 v[196:197], v188
	v_cvt_pk_f32_fp8_sdwa v[198:199], v188 src0_sel:WORD_1
	v_cvt_pk_f32_fp8_e32 v[200:201], v189
	v_cvt_pk_f32_fp8_sdwa v[202:203], v189 src0_sel:WORD_1
	v_cvt_pk_f32_fp8_e32 v[216:217], v190
	v_cvt_pk_f32_fp8_sdwa v[218:219], v190 src0_sel:WORD_1
	v_cvt_pk_f32_fp8_e32 v[220:221], v191
	v_cvt_pk_f32_fp8_sdwa v[222:223], v191 src0_sel:WORD_1
	v_pk_fma_f32 v[6:7], v[46:47], v[196:197], v[6:7] op_sel:[1,0,0]
	v_pk_fma_f32 v[8:9], v[46:47], v[198:199], v[8:9] op_sel:[1,0,0]
	v_pk_fma_f32 v[10:11], v[46:47], v[200:201], v[10:11] op_sel:[1,0,0]
	v_pk_fma_f32 v[12:13], v[46:47], v[202:203], v[12:13] op_sel:[1,0,0]
	v_pk_fma_f32 v[14:15], v[46:47], v[216:217], v[14:15] op_sel:[1,0,0]
	v_pk_fma_f32 v[16:17], v[46:47], v[218:219], v[16:17] op_sel:[1,0,0]
	v_pk_fma_f32 v[2:3], v[46:47], v[220:221], v[2:3] op_sel:[1,0,0]
	v_pk_fma_f32 v[4:5], v[46:47], v[222:223], v[4:5] op_sel:[1,0,0]
	v_readfirstlane_b32 s30, v158
	s_ashr_i32 s31, s30, 31
	s_lshl_b64 s[30:31], s[30:31], 10
	v_lshl_add_u64 v[162:163], v[122:123], 0, s[30:31]
	global_load_dwordx4 v[188:191], v[162:163], off
	s_waitcnt vmcnt(15)
;     ...
;     for (int j0 = 0; j0 < NTL * 16; j0 += 16) {
;         u32x4_t w[16]; float cj[16];
; #pragma unroll
;         for (int jj = 0; jj < 16; ++jj) { const u32x2_t pr = pl[j0 + jj]; const int ej = __builtin_amdgcn_readfirstlane((int)pr.x); cj[jj] = __uint_as_float(pr.y);
;             w[jj] = *(const u32x4_t*)(v8 + (size_t)ej * D + 16 * lane); }
; #pragma unroll
;         for (int jj = 0; jj < 16; ++jj) { const float c = cj[jj];
; #pragma unroll
;             for (int q = 0; q < 4; ++q) { const f32x2_t lo = __builtin_amdgcn_cvt_pk_f32_fp8((int)w[jj][q], false), hi = __builtin_amdgcn_cvt_pk_f32_fp8((int)w[jj][q], true);
;                 o[4 * q] += c * lo[0]; o[4 * q + 1] += c * lo[1]; o[4 * q + 2] += c * hi[0]; o[4 * q + 3] += c * hi[1]; } }
;     }
	v_cvt_pk_f32_fp8_e32 v[196:197], v192
	v_cvt_pk_f32_fp8_sdwa v[198:199], v192 src0_sel:WORD_1
	v_cvt_pk_f32_fp8_e32 v[200:201], v193
	v_cvt_pk_f32_fp8_sdwa v[202:203], v193 src0_sel:WORD_1
	v_cvt_pk_f32_fp8_e32 v[216:217], v194
	v_cvt_pk_f32_fp8_sdwa v[218:219], v194 src0_sel:WORD_1
	v_cvt_pk_f32_fp8_e32 v[220:221], v195
	v_cvt_pk_f32_fp8_sdwa v[222:223], v195 src0_sel:WORD_1
	v_pk_fma_f32 v[6:7], v[48:49], v[196:197], v[6:7] op_sel:[1,0,0]
	v_pk_fma_f32 v[8:9], v[48:49], v[198:199], v[8:9] op_sel:[1,0,0]
	v_pk_fma_f32 v[10:11], v[48:49], v[200:201], v[10:11] op_sel:[1,0,0]
	v_pk_fma_f32 v[12:13], v[48:49], v[202:203], v[12:13] op_sel:[1,0,0]
	v_pk_fma_f32 v[14:15], v[48:49], v[216:217], v[14:15] op_sel:[1,0,0]
	v_pk_fma_f32 v[16:17], v[48:49], v[218:219], v[16:17] op_sel:[1,0,0]
	v_pk_fma_f32 v[2:3], v[48:49], v[220:221], v[2:3] op_sel:[1,0,0]
	v_pk_fma_f32 v[4:5], v[48:49], v[222:223], v[4:5] op_sel:[1,0,0]
	v_readfirstlane_b32 s30, v160
	s_ashr_i32 s31, s30, 31
	s_lshl_b64 s[30:31], s[30:31], 10
	v_lshl_add_u64 v[162:163], v[122:123], 0, s[30:31]
	global_load_dwordx4 v[192:195], v[162:163], off
	s_waitcnt vmcnt(15)
	v_cvt_pk_f32_fp8_e32 v[196:197], v68
	v_cvt_pk_f32_fp8_sdwa v[198:199], v68 src0_sel:WORD_1
	v_cvt_pk_f32_fp8_e32 v[200:201], v69
	v_cvt_pk_f32_fp8_sdwa v[202:203], v69 src0_sel:WORD_1
	v_cvt_pk_f32_fp8_e32 v[216:217], v70
	v_cvt_pk_f32_fp8_sdwa v[218:219], v70 src0_sel:WORD_1
	v_cvt_pk_f32_fp8_e32 v[220:221], v71
	v_cvt_pk_f32_fp8_sdwa v[222:223], v71 src0_sel:WORD_1
	v_pk_fma_f32 v[6:7], v[130:131], v[196:197], v[6:7] op_sel:[1,0,0]
	v_pk_fma_f32 v[8:9], v[130:131], v[198:199], v[8:9] op_sel:[1,0,0]
	v_pk_fma_f32 v[10:11], v[130:131], v[200:201], v[10:11] op_sel:[1,0,0]
	v_pk_fma_f32 v[12:13], v[130:131], v[202:203], v[12:13] op_sel:[1,0,0]
	v_pk_fma_f32 v[14:15], v[130:131], v[216:217], v[14:15] op_sel:[1,0,0]
	v_pk_fma_f32 v[16:17], v[130:131], v[218:219], v[16:17] op_sel:[1,0,0]
	v_pk_fma_f32 v[2:3], v[130:131], v[220:221], v[2:3] op_sel:[1,0,0]
	v_pk_fma_f32 v[4:5], v[130:131], v[222:223], v[4:5] op_sel:[1,0,0]
	s_waitcnt vmcnt(14)
	v_cvt_pk_f32_fp8_e32 v[196:197], v72
	v_cvt_pk_f32_fp8_sdwa v[198:199], v72 src0_sel:WORD_1
	v_cvt_pk_f32_fp8_e32 v[200:201], v73
	v_cvt_pk_f32_fp8_sdwa v[202:203], v73 src0_sel:WORD_1
	v_cvt_pk_f32_fp8_e32 v[216:217], v74
	v_cvt_pk_f32_fp8_sdwa v[218:219], v74 src0_sel:WORD_1
	v_cvt_pk_f32_fp8_e32 v[220:221], v75
	v_cvt_pk_f32_fp8_sdwa v[222:223], v75 src0_sel:WORD_1
	v_pk_fma_f32 v[6:7], v[132:133], v[196:197], v[6:7] op_sel:[1,0,0]
	v_pk_fma_f32 v[8:9], v[132:133], v[198:199], v[8:9] op_sel:[1,0,0]
	v_pk_fma_f32 v[10:11], v[132:133], v[200:201], v[10:11] op_sel:[1,0,0]
	v_pk_fma_f32 v[12:13], v[132:133], v[202:203], v[12:13] op_sel:[1,0,0]
	v_pk_fma_f32 v[14:15], v[132:133], v[216:217], v[14:15] op_sel:[1,0,0]
	v_pk_fma_f32 v[16:17], v[132:133], v[218:219], v[16:17] op_sel:[1,0,0]
	v_pk_fma_f32 v[2:3], v[132:133], v[220:221], v[2:3] op_sel:[1,0,0]
	v_pk_fma_f32 v[4:5], v[132:133], v[222:223], v[4:5] op_sel:[1,0,0]
	s_waitcnt vmcnt(13)
	v_cvt_pk_f32_fp8_e32 v[196:197], v76
	v_cvt_pk_f32_fp8_sdwa v[198:199], v76 src0_sel:WORD_1
	v_cvt_pk_f32_fp8_e32 v[200:201], v77
	v_cvt_pk_f32_fp8_sdwa v[202:203], v77 src0_sel:WORD_1
	v_cvt_pk_f32_fp8_e32 v[216:217], v78
	v_cvt_pk_f32_fp8_sdwa v[218:219], v78 src0_sel:WORD_1
	v_cvt_pk_f32_fp8_e32 v[220:221], v79
	v_cvt_pk_f32_fp8_sdwa v[222:223], v79 src0_sel:WORD_1
	v_pk_fma_f32 v[6:7], v[134:135], v[196:197], v[6:7] op_sel:[1,0,0]
	v_pk_fma_f32 v[8:9], v[134:135], v[198:199], v[8:9] op_sel:[1,0,0]
	v_pk_fma_f32 v[10:11], v[134:135], v[200:201], v[10:11] op_sel:[1,0,0]
	v_pk_fma_f32 v[12:13], v[134:135], v[202:203], v[12:13] op_sel:[1,0,0]
	v_pk_fma_f32 v[14:15], v[134:135], v[216:217], v[14:15] op_sel:[1,0,0]
	v_pk_fma_f32 v[16:17], v[134:135], v[218:219], v[16:17] op_sel:[1,0,0]
	v_pk_fma_f32 v[2:3], v[134:135], v[220:221], v[2:3] op_sel:[1,0,0]
	v_pk_fma_f32 v[4:5], v[134:135], v[222:223], v[4:5] op_sel:[1,0,0]
	s_waitcnt vmcnt(12)
	v_cvt_pk_f32_fp8_e32 v[196:197], v80
	v_cvt_pk_f32_fp8_sdwa v[198:199], v80 src0_sel:WORD_1
	v_cvt_pk_f32_fp8_e32 v[200:201], v81
	v_cvt_pk_f32_fp8_sdwa v[202:203], v81 src0_sel:WORD_1
	v_cvt_pk_f32_fp8_e32 v[216:217], v82
	v_cvt_pk_f32_fp8_sdwa v[218:219], v82 src0_sel:WORD_1
	v_cvt_pk_f32_fp8_e32 v[220:221], v83
	v_cvt_pk_f32_fp8_sdwa v[222:223], v83 src0_sel:WORD_1
	v_pk_fma_f32 v[6:7], v[136:137], v[196:197], v[6:7] op_sel:[1,0,0]
	v_pk_fma_f32 v[8:9], v[136:137], v[198:199], v[8:9] op_sel:[1,0,0]
	v_pk_fma_f32 v[10:11], v[136:137], v[200:201], v[10:11] op_sel:[1,0,0]
	v_pk_fma_f32 v[12:13], v[136:137], v[202:203], v[12:13] op_sel:[1,0,0]
	v_pk_fma_f32 v[14:15], v[136:137], v[216:217], v[14:15] op_sel:[1,0,0]
	v_pk_fma_f32 v[16:17], v[136:137], v[218:219], v[16:17] op_sel:[1,0,0]
	v_pk_fma_f32 v[2:3], v[136:137], v[220:221], v[2:3] op_sel:[1,0,0]
	v_pk_fma_f32 v[4:5], v[136:137], v[222:223], v[4:5] op_sel:[1,0,0]
	s_waitcnt vmcnt(11)
	v_cvt_pk_f32_fp8_e32 v[196:197], v84
	v_cvt_pk_f32_fp8_sdwa v[198:199], v84 src0_sel:WORD_1
	v_cvt_pk_f32_fp8_e32 v[200:201], v85
	v_cvt_pk_f32_fp8_sdwa v[202:203], v85 src0_sel:WORD_1
	v_cvt_pk_f32_fp8_e32 v[216:217], v86
	v_cvt_pk_f32_fp8_sdwa v[218:219], v86 src0_sel:WORD_1
	v_cvt_pk_f32_fp8_e32 v[220:221], v87
	v_cvt_pk_f32_fp8_sdwa v[222:223], v87 src0_sel:WORD_1
	v_pk_fma_f32 v[6:7], v[138:139], v[196:197], v[6:7] op_sel:[1,0,0]
	v_pk_fma_f32 v[8:9], v[138:139], v[198:199], v[8:9] op_sel:[1,0,0]
	v_pk_fma_f32 v[10:11], v[138:139], v[200:201], v[10:11] op_sel:[1,0,0]
	v_pk_fma_f32 v[12:13], v[138:139], v[202:203], v[12:13] op_sel:[1,0,0]
	v_pk_fma_f32 v[14:15], v[138:139], v[216:217], v[14:15] op_sel:[1,0,0]
	v_pk_fma_f32 v[16:17], v[138:139], v[218:219], v[16:17] op_sel:[1,0,0]
	v_pk_fma_f32 v[2:3], v[138:139], v[220:221], v[2:3] op_sel:[1,0,0]
	v_pk_fma_f32 v[4:5], v[138:139], v[222:223], v[4:5] op_sel:[1,0,0]
	s_waitcnt vmcnt(10)
;     ...
;     for (int j0 = 0; j0 < NTL * 16; j0 += 16) {
;         u32x4_t w[16]; float cj[16];
; #pragma unroll
;         for (int jj = 0; jj < 16; ++jj) { const u32x2_t pr = pl[j0 + jj]; const int ej = __builtin_amdgcn_readfirstlane((int)pr.x); cj[jj] = __uint_as_float(pr.y);
;             w[jj] = *(const u32x4_t*)(v8 + (size_t)ej * D + 16 * lane); }
; #pragma unroll
;         for (int jj = 0; jj < 16; ++jj) { const float c = cj[jj];
; #pragma unroll
;             for (int q = 0; q < 4; ++q) { const f32x2_t lo = __builtin_amdgcn_cvt_pk_f32_fp8((int)w[jj][q], false), hi = __builtin_amdgcn_cvt_pk_f32_fp8((int)w[jj][q], true);
;                 o[4 * q] += c * lo[0]; o[4 * q + 1] += c * lo[1]; o[4 * q + 2] += c * hi[0]; o[4 * q + 3] += c * hi[1]; } }
;     }
	v_cvt_pk_f32_fp8_e32 v[196:197], v88
	v_cvt_pk_f32_fp8_sdwa v[198:199], v88 src0_sel:WORD_1
	v_cvt_pk_f32_fp8_e32 v[200:201], v89
	v_cvt_pk_f32_fp8_sdwa v[202:203], v89 src0_sel:WORD_1
	v_cvt_pk_f32_fp8_e32 v[216:217], v90
	v_cvt_pk_f32_fp8_sdwa v[218:219], v90 src0_sel:WORD_1
	v_cvt_pk_f32_fp8_e32 v[220:221], v91
	v_cvt_pk_f32_fp8_sdwa v[222:223], v91 src0_sel:WORD_1
	v_pk_fma_f32 v[6:7], v[140:141], v[196:197], v[6:7] op_sel:[1,0,0]
	v_pk_fma_f32 v[8:9], v[140:141], v[198:199], v[8:9] op_sel:[1,0,0]
	v_pk_fma_f32 v[10:11], v[140:141], v[200:201], v[10:11] op_sel:[1,0,0]
	v_pk_fma_f32 v[12:13], v[140:141], v[202:203], v[12:13] op_sel:[1,0,0]
	v_pk_fma_f32 v[14:15], v[140:141], v[216:217], v[14:15] op_sel:[1,0,0]
	v_pk_fma_f32 v[16:17], v[140:141], v[218:219], v[16:17] op_sel:[1,0,0]
	v_pk_fma_f32 v[2:3], v[140:141], v[220:221], v[2:3] op_sel:[1,0,0]
	v_pk_fma_f32 v[4:5], v[140:141], v[222:223], v[4:5] op_sel:[1,0,0]
	s_waitcnt vmcnt(9)
	v_cvt_pk_f32_fp8_e32 v[196:197], v92
	v_cvt_pk_f32_fp8_sdwa v[198:199], v92 src0_sel:WORD_1
	v_cvt_pk_f32_fp8_e32 v[200:201], v93
	v_cvt_pk_f32_fp8_sdwa v[202:203], v93 src0_sel:WORD_1
	v_cvt_pk_f32_fp8_e32 v[216:217], v94
	v_cvt_pk_f32_fp8_sdwa v[218:219], v94 src0_sel:WORD_1
	v_cvt_pk_f32_fp8_e32 v[220:221], v95
	v_cvt_pk_f32_fp8_sdwa v[222:223], v95 src0_sel:WORD_1
	v_pk_fma_f32 v[6:7], v[142:143], v[196:197], v[6:7] op_sel:[1,0,0]
	v_pk_fma_f32 v[8:9], v[142:143], v[198:199], v[8:9] op_sel:[1,0,0]
	v_pk_fma_f32 v[10:11], v[142:143], v[200:201], v[10:11] op_sel:[1,0,0]
	v_pk_fma_f32 v[12:13], v[142:143], v[202:203], v[12:13] op_sel:[1,0,0]
	v_pk_fma_f32 v[14:15], v[142:143], v[216:217], v[14:15] op_sel:[1,0,0]
	v_pk_fma_f32 v[16:17], v[142:143], v[218:219], v[16:17] op_sel:[1,0,0]
	v_pk_fma_f32 v[2:3], v[142:143], v[220:221], v[2:3] op_sel:[1,0,0]
	v_pk_fma_f32 v[4:5], v[142:143], v[222:223], v[4:5] op_sel:[1,0,0]
	s_waitcnt vmcnt(8)
	v_cvt_pk_f32_fp8_e32 v[196:197], v96
	v_cvt_pk_f32_fp8_sdwa v[198:199], v96 src0_sel:WORD_1
	v_cvt_pk_f32_fp8_e32 v[200:201], v97
	v_cvt_pk_f32_fp8_sdwa v[202:203], v97 src0_sel:WORD_1
	v_cvt_pk_f32_fp8_e32 v[216:217], v98
	v_cvt_pk_f32_fp8_sdwa v[218:219], v98 src0_sel:WORD_1
	v_cvt_pk_f32_fp8_e32 v[220:221], v99
	v_cvt_pk_f32_fp8_sdwa v[222:223], v99 src0_sel:WORD_1
	v_pk_fma_f32 v[6:7], v[144:145], v[196:197], v[6:7] op_sel:[1,0,0]
	v_pk_fma_f32 v[8:9], v[144:145], v[198:199], v[8:9] op_sel:[1,0,0]
	v_pk_fma_f32 v[10:11], v[144:145], v[200:201], v[10:11] op_sel:[1,0,0]
	v_pk_fma_f32 v[12:13], v[144:145], v[202:203], v[12:13] op_sel:[1,0,0]
	v_pk_fma_f32 v[14:15], v[144:145], v[216:217], v[14:15] op_sel:[1,0,0]
	v_pk_fma_f32 v[16:17], v[144:145], v[218:219], v[16:17] op_sel:[1,0,0]
	v_pk_fma_f32 v[2:3], v[144:145], v[220:221], v[2:3] op_sel:[1,0,0]
	v_pk_fma_f32 v[4:5], v[144:145], v[222:223], v[4:5] op_sel:[1,0,0]
	s_waitcnt vmcnt(7)
	v_cvt_pk_f32_fp8_e32 v[196:197], v100
	v_cvt_pk_f32_fp8_sdwa v[198:199], v100 src0_sel:WORD_1
	v_cvt_pk_f32_fp8_e32 v[200:201], v101
	v_cvt_pk_f32_fp8_sdwa v[202:203], v101 src0_sel:WORD_1
	v_cvt_pk_f32_fp8_e32 v[216:217], v102
	v_cvt_pk_f32_fp8_sdwa v[218:219], v102 src0_sel:WORD_1
	v_cvt_pk_f32_fp8_e32 v[220:221], v103
	v_cvt_pk_f32_fp8_sdwa v[222:223], v103 src0_sel:WORD_1
	v_pk_fma_f32 v[6:7], v[146:147], v[196:197], v[6:7] op_sel:[1,0,0]
	v_pk_fma_f32 v[8:9], v[146:147], v[198:199], v[8:9] op_sel:[1,0,0]
	v_pk_fma_f32 v[10:11], v[146:147], v[200:201], v[10:11] op_sel:[1,0,0]
	v_pk_fma_f32 v[12:13], v[146:147], v[202:203], v[12:13] op_sel:[1,0,0]
	v_pk_fma_f32 v[14:15], v[146:147], v[216:217], v[14:15] op_sel:[1,0,0]
	v_pk_fma_f32 v[16:17], v[146:147], v[218:219], v[16:17] op_sel:[1,0,0]
	v_pk_fma_f32 v[2:3], v[146:147], v[220:221], v[2:3] op_sel:[1,0,0]
	v_pk_fma_f32 v[4:5], v[146:147], v[222:223], v[4:5] op_sel:[1,0,0]
	s_waitcnt vmcnt(6)
	v_cvt_pk_f32_fp8_e32 v[196:197], v104
	v_cvt_pk_f32_fp8_sdwa v[198:199], v104 src0_sel:WORD_1
	v_cvt_pk_f32_fp8_e32 v[200:201], v105
	v_cvt_pk_f32_fp8_sdwa v[202:203], v105 src0_sel:WORD_1
	v_cvt_pk_f32_fp8_e32 v[216:217], v106
	v_cvt_pk_f32_fp8_sdwa v[218:219], v106 src0_sel:WORD_1
	v_cvt_pk_f32_fp8_e32 v[220:221], v107
	v_cvt_pk_f32_fp8_sdwa v[222:223], v107 src0_sel:WORD_1
	v_pk_fma_f32 v[6:7], v[148:149], v[196:197], v[6:7] op_sel:[1,0,0]
	v_pk_fma_f32 v[8:9], v[148:149], v[198:199], v[8:9] op_sel:[1,0,0]
	v_pk_fma_f32 v[10:11], v[148:149], v[200:201], v[10:11] op_sel:[1,0,0]
	v_pk_fma_f32 v[12:13], v[148:149], v[202:203], v[12:13] op_sel:[1,0,0]
	v_pk_fma_f32 v[14:15], v[148:149], v[216:217], v[14:15] op_sel:[1,0,0]
	v_pk_fma_f32 v[16:17], v[148:149], v[218:219], v[16:17] op_sel:[1,0,0]
	v_pk_fma_f32 v[2:3], v[148:149], v[220:221], v[2:3] op_sel:[1,0,0]
	v_pk_fma_f32 v[4:5], v[148:149], v[222:223], v[4:5] op_sel:[1,0,0]
	s_waitcnt vmcnt(5)
	v_cvt_pk_f32_fp8_e32 v[196:197], v108
	v_cvt_pk_f32_fp8_sdwa v[198:199], v108 src0_sel:WORD_1
	v_cvt_pk_f32_fp8_e32 v[200:201], v109
	v_cvt_pk_f32_fp8_sdwa v[202:203], v109 src0_sel:WORD_1
	v_cvt_pk_f32_fp8_e32 v[216:217], v110
	v_cvt_pk_f32_fp8_sdwa v[218:219], v110 src0_sel:WORD_1
	v_cvt_pk_f32_fp8_e32 v[220:221], v111
	v_cvt_pk_f32_fp8_sdwa v[222:223], v111 src0_sel:WORD_1
	v_pk_fma_f32 v[6:7], v[150:151], v[196:197], v[6:7] op_sel:[1,0,0]
	v_pk_fma_f32 v[8:9], v[150:151], v[198:199], v[8:9] op_sel:[1,0,0]
	v_pk_fma_f32 v[10:11], v[150:151], v[200:201], v[10:11] op_sel:[1,0,0]
	v_pk_fma_f32 v[12:13], v[150:151], v[202:203], v[12:13] op_sel:[1,0,0]
	v_pk_fma_f32 v[14:15], v[150:151], v[216:217], v[14:15] op_sel:[1,0,0]
	v_pk_fma_f32 v[16:17], v[150:151], v[218:219], v[16:17] op_sel:[1,0,0]
	v_pk_fma_f32 v[2:3], v[150:151], v[220:221], v[2:3] op_sel:[1,0,0]
	v_pk_fma_f32 v[4:5], v[150:151], v[222:223], v[4:5] op_sel:[1,0,0]
	s_waitcnt vmcnt(4)
; #define LAS __attribute__((address_space(3)))
;     ...
;     for (int j0 = 0; j0 < NTL * 16; j0 += 16) {
;         u32x4_t w[16]; float cj[16];
; #pragma unroll
;         for (int jj = 0; jj < 16; ++jj) { const u32x2_t pr = pl[j0 + jj]; const int ej = __builtin_amdgcn_readfirstlane((int)pr.x); cj[jj] = __uint_as_float(pr.y);
;             w[jj] = *(const u32x4_t*)(v8 + (size_t)ej * D + 16 * lane); }
; #pragma unroll
;         for (int jj = 0; jj < 16; ++jj) { const float c = cj[jj];
; #pragma unroll
;             for (int q = 0; q < 4; ++q) { const f32x2_t lo = __builtin_amdgcn_cvt_pk_f32_fp8((int)w[jj][q], false), hi = __builtin_amdgcn_cvt_pk_f32_fp8((int)w[jj][q], true);
;                 o[4 * q] += c * lo[0]; o[4 * q + 1] += c * lo[1]; o[4 * q + 2] += c * hi[0]; o[4 * q + 3] += c * hi[1]; } }
;     }
;     if (NTL < 8) {
;         if (half == 1) {
; #pragma unroll
;             for (int q = 0; q < 4; ++q) *(LAS f32x4_t*)(xch + lane * 16 + 4 * q) = (f32x4_t){o[4 * q], o[4 * q + 1], o[4 * q + 2], o[4 * q + 3]};
;         }
	v_cvt_pk_f32_fp8_e32 v[196:197], v112
	v_cvt_pk_f32_fp8_sdwa v[198:199], v112 src0_sel:WORD_1
	v_cvt_pk_f32_fp8_e32 v[200:201], v113
	v_cvt_pk_f32_fp8_sdwa v[202:203], v113 src0_sel:WORD_1
	v_cvt_pk_f32_fp8_e32 v[216:217], v114
	v_cvt_pk_f32_fp8_sdwa v[218:219], v114 src0_sel:WORD_1
	v_cvt_pk_f32_fp8_e32 v[220:221], v115
	v_cvt_pk_f32_fp8_sdwa v[222:223], v115 src0_sel:WORD_1
	v_pk_fma_f32 v[6:7], v[152:153], v[196:197], v[6:7] op_sel:[1,0,0]
	v_pk_fma_f32 v[8:9], v[152:153], v[198:199], v[8:9] op_sel:[1,0,0]
	v_pk_fma_f32 v[10:11], v[152:153], v[200:201], v[10:11] op_sel:[1,0,0]
	v_pk_fma_f32 v[12:13], v[152:153], v[202:203], v[12:13] op_sel:[1,0,0]
	v_pk_fma_f32 v[14:15], v[152:153], v[216:217], v[14:15] op_sel:[1,0,0]
	v_pk_fma_f32 v[16:17], v[152:153], v[218:219], v[16:17] op_sel:[1,0,0]
	v_pk_fma_f32 v[2:3], v[152:153], v[220:221], v[2:3] op_sel:[1,0,0]
	v_pk_fma_f32 v[4:5], v[152:153], v[222:223], v[4:5] op_sel:[1,0,0]
	s_waitcnt vmcnt(3)
	v_cvt_pk_f32_fp8_e32 v[196:197], v180
	v_cvt_pk_f32_fp8_sdwa v[198:199], v180 src0_sel:WORD_1
	v_cvt_pk_f32_fp8_e32 v[200:201], v181
	v_cvt_pk_f32_fp8_sdwa v[202:203], v181 src0_sel:WORD_1
	v_cvt_pk_f32_fp8_e32 v[216:217], v182
	v_cvt_pk_f32_fp8_sdwa v[218:219], v182 src0_sel:WORD_1
	v_cvt_pk_f32_fp8_e32 v[220:221], v183
	v_cvt_pk_f32_fp8_sdwa v[222:223], v183 src0_sel:WORD_1
	v_pk_fma_f32 v[6:7], v[154:155], v[196:197], v[6:7] op_sel:[1,0,0]
	v_pk_fma_f32 v[8:9], v[154:155], v[198:199], v[8:9] op_sel:[1,0,0]
	v_pk_fma_f32 v[10:11], v[154:155], v[200:201], v[10:11] op_sel:[1,0,0]
	v_pk_fma_f32 v[12:13], v[154:155], v[202:203], v[12:13] op_sel:[1,0,0]
	v_pk_fma_f32 v[14:15], v[154:155], v[216:217], v[14:15] op_sel:[1,0,0]
	v_pk_fma_f32 v[16:17], v[154:155], v[218:219], v[16:17] op_sel:[1,0,0]
	v_pk_fma_f32 v[2:3], v[154:155], v[220:221], v[2:3] op_sel:[1,0,0]
	v_pk_fma_f32 v[4:5], v[154:155], v[222:223], v[4:5] op_sel:[1,0,0]
	s_waitcnt vmcnt(2)
	v_cvt_pk_f32_fp8_e32 v[196:197], v184
	v_cvt_pk_f32_fp8_sdwa v[198:199], v184 src0_sel:WORD_1
	v_cvt_pk_f32_fp8_e32 v[200:201], v185
	v_cvt_pk_f32_fp8_sdwa v[202:203], v185 src0_sel:WORD_1
	v_cvt_pk_f32_fp8_e32 v[216:217], v186
	v_cvt_pk_f32_fp8_sdwa v[218:219], v186 src0_sel:WORD_1
	v_cvt_pk_f32_fp8_e32 v[220:221], v187
	v_cvt_pk_f32_fp8_sdwa v[222:223], v187 src0_sel:WORD_1
	v_pk_fma_f32 v[6:7], v[156:157], v[196:197], v[6:7] op_sel:[1,0,0]
	v_pk_fma_f32 v[8:9], v[156:157], v[198:199], v[8:9] op_sel:[1,0,0]
	v_pk_fma_f32 v[10:11], v[156:157], v[200:201], v[10:11] op_sel:[1,0,0]
	v_pk_fma_f32 v[12:13], v[156:157], v[202:203], v[12:13] op_sel:[1,0,0]
	v_pk_fma_f32 v[14:15], v[156:157], v[216:217], v[14:15] op_sel:[1,0,0]
	v_pk_fma_f32 v[16:17], v[156:157], v[218:219], v[16:17] op_sel:[1,0,0]
	v_pk_fma_f32 v[2:3], v[156:157], v[220:221], v[2:3] op_sel:[1,0,0]
	v_pk_fma_f32 v[4:5], v[156:157], v[222:223], v[4:5] op_sel:[1,0,0]
	s_waitcnt vmcnt(1)
	v_cvt_pk_f32_fp8_e32 v[196:197], v188
	v_cvt_pk_f32_fp8_sdwa v[198:199], v188 src0_sel:WORD_1
	v_cvt_pk_f32_fp8_e32 v[200:201], v189
	v_cvt_pk_f32_fp8_sdwa v[202:203], v189 src0_sel:WORD_1
	v_cvt_pk_f32_fp8_e32 v[216:217], v190
	v_cvt_pk_f32_fp8_sdwa v[218:219], v190 src0_sel:WORD_1
	v_cvt_pk_f32_fp8_e32 v[220:221], v191
	v_cvt_pk_f32_fp8_sdwa v[222:223], v191 src0_sel:WORD_1
	v_pk_fma_f32 v[6:7], v[158:159], v[196:197], v[6:7] op_sel:[1,0,0]
	v_pk_fma_f32 v[8:9], v[158:159], v[198:199], v[8:9] op_sel:[1,0,0]
	v_pk_fma_f32 v[10:11], v[158:159], v[200:201], v[10:11] op_sel:[1,0,0]
	v_pk_fma_f32 v[12:13], v[158:159], v[202:203], v[12:13] op_sel:[1,0,0]
	v_pk_fma_f32 v[14:15], v[158:159], v[216:217], v[14:15] op_sel:[1,0,0]
	v_pk_fma_f32 v[16:17], v[158:159], v[218:219], v[16:17] op_sel:[1,0,0]
	v_pk_fma_f32 v[2:3], v[158:159], v[220:221], v[2:3] op_sel:[1,0,0]
	v_pk_fma_f32 v[4:5], v[158:159], v[222:223], v[4:5] op_sel:[1,0,0]
	s_waitcnt vmcnt(0)
	v_cvt_pk_f32_fp8_e32 v[196:197], v192
	v_cvt_pk_f32_fp8_sdwa v[198:199], v192 src0_sel:WORD_1
	v_cvt_pk_f32_fp8_e32 v[200:201], v193
	v_cvt_pk_f32_fp8_sdwa v[202:203], v193 src0_sel:WORD_1
	v_cvt_pk_f32_fp8_e32 v[216:217], v194
	v_cvt_pk_f32_fp8_sdwa v[218:219], v194 src0_sel:WORD_1
	v_cvt_pk_f32_fp8_e32 v[220:221], v195
	v_cvt_pk_f32_fp8_sdwa v[222:223], v195 src0_sel:WORD_1
	v_pk_fma_f32 v[6:7], v[160:161], v[196:197], v[6:7] op_sel:[1,0,0]
	v_pk_fma_f32 v[8:9], v[160:161], v[198:199], v[8:9] op_sel:[1,0,0]
	v_pk_fma_f32 v[10:11], v[160:161], v[200:201], v[10:11] op_sel:[1,0,0]
	v_pk_fma_f32 v[12:13], v[160:161], v[202:203], v[12:13] op_sel:[1,0,0]
	v_pk_fma_f32 v[14:15], v[160:161], v[216:217], v[14:15] op_sel:[1,0,0]
	v_pk_fma_f32 v[16:17], v[160:161], v[218:219], v[16:17] op_sel:[1,0,0]
	v_pk_fma_f32 v[2:3], v[160:161], v[220:221], v[2:3] op_sel:[1,0,0]
	v_pk_fma_f32 v[4:5], v[160:161], v[222:223], v[4:5] op_sel:[1,0,0]
	v_readlane_b32 s26, v252, 22
	v_readlane_b32 s27, v252, 23
	s_andn2_b64 vcc, exec, s[26:27]
	s_cbranch_vccnz .LBB0_1141
	ds_write_b128 v128, v[6:9]
	ds_write_b128 v128, v[10:13] offset:16
	ds_write_b128 v128, v[14:17] offset:32
	ds_write_b128 v128, v[2:5] offset:48
